# GEMM K-loops: transposed 32-MFMA snake (runs share the B-fragment operand, srcA) - compare with v36
# baseline (speedup 1.0000x reference)
.LBB0_261:
	s_add_u32 s0, s76, 0xfff80080
	s_addc_u32 s1, s77, -1
	s_and_b64 s[84:85], s[84:85], exec
	s_cselect_b32 vcc_hi, s22, s1
	s_cselect_b32 vcc_lo, s23, s0
	s_cselect_b32 s85, s49, s58
	s_cselect_b32 s84, s57, s51
	s_add_i32 s0, 0, 0x10000
	s_add_i32 s1, 0, 0x14000
	v_add_u32_e32 v158, s0, v176
	v_add_u32_e32 v174, s1, v176
	ds_read_b128 v[146:149], v158
	ds_read_b128 v[150:153], v158 offset:1024
	ds_read_b128 v[154:157], v158 offset:2048
	ds_read_b128 v[158:161], v158 offset:3072
	ds_read_b128 v[162:165], v174
	ds_read_b128 v[166:169], v174 offset:1024
	ds_read_b128 v[170:173], v174 offset:2048
	ds_read_b128 v[178:181], v174 offset:3072
	v_lshl_add_u64 v[174:175], s[76:77], 0, v[138:139]
	s_add_i32 m0, s21, 0xc000
	ds_read_b128 v[182:185], v177
	ds_read_b128 v[186:189], v177 offset:1024
	ds_read_b128 v[190:193], v177 offset:2048
	ds_read_b128 v[204:207], v177 offset:3072
	ds_read_b128 v[208:211], v177 offset:4096
	ds_read_b128 v[212:215], v177 offset:5120
	ds_read_b128 v[216:219], v177 offset:6144
	ds_read_b128 v[220:223], v177 offset:7168
	global_load_lds_dwordx4 v[174:175], off
	v_lshl_add_u64 v[174:175], s[76:77], 0, v[140:141]
	s_add_i32 m0, s21, 0xe000
	s_nop 0
	global_load_lds_dwordx4 v[174:175], off
	s_waitcnt vmcnt(8)
	s_waitcnt lgkmcnt(0)
	s_barrier
	s_setprio 1
	s_waitcnt lgkmcnt(0)
	v_mfma_f32_16x16x32_bf16 v[126:129], v[146:149], v[182:185], v[126:129]
	v_mfma_f32_16x16x32_bf16 v[126:129], v[150:153], v[186:189], v[126:129]
	v_mfma_f32_16x16x32_bf16 v[110:113], v[150:153], v[204:207], v[110:113]
	v_mfma_f32_16x16x32_bf16 v[110:113], v[146:149], v[190:193], v[110:113]
	v_mfma_f32_16x16x32_bf16 v[94:97], v[146:149], v[208:211], v[94:97]
	v_mfma_f32_16x16x32_bf16 v[94:97], v[150:153], v[212:215], v[94:97]
	v_mfma_f32_16x16x32_bf16 v[78:81], v[150:153], v[220:223], v[78:81]
	v_mfma_f32_16x16x32_bf16 v[78:81], v[146:149], v[216:219], v[78:81]
	v_mfma_f32_16x16x32_bf16 v[74:77], v[154:157], v[216:219], v[74:77]
	v_mfma_f32_16x16x32_bf16 v[74:77], v[158:161], v[220:223], v[74:77]
	v_mfma_f32_16x16x32_bf16 v[90:93], v[158:161], v[212:215], v[90:93]
	v_mfma_f32_16x16x32_bf16 v[90:93], v[154:157], v[208:211], v[90:93]
	v_mfma_f32_16x16x32_bf16 v[106:109], v[154:157], v[190:193], v[106:109]
	v_mfma_f32_16x16x32_bf16 v[106:109], v[158:161], v[204:207], v[106:109]
	v_mfma_f32_16x16x32_bf16 v[122:125], v[158:161], v[186:189], v[122:125]
	v_mfma_f32_16x16x32_bf16 v[122:125], v[154:157], v[182:185], v[122:125]
	v_mfma_f32_16x16x32_bf16 v[118:121], v[162:165], v[182:185], v[118:121]
	v_mfma_f32_16x16x32_bf16 v[118:121], v[166:169], v[186:189], v[118:121]
	v_mfma_f32_16x16x32_bf16 v[102:105], v[166:169], v[204:207], v[102:105]
	v_mfma_f32_16x16x32_bf16 v[102:105], v[162:165], v[190:193], v[102:105]
	v_mfma_f32_16x16x32_bf16 v[86:89], v[162:165], v[208:211], v[86:89]
	v_mfma_f32_16x16x32_bf16 v[86:89], v[166:169], v[212:215], v[86:89]
	v_mfma_f32_16x16x32_bf16 v[70:73], v[166:169], v[220:223], v[70:73]
	v_mfma_f32_16x16x32_bf16 v[70:73], v[162:165], v[216:219], v[70:73]
	v_mfma_f32_16x16x32_bf16 v[66:69], v[170:173], v[216:219], v[66:69]
	v_mfma_f32_16x16x32_bf16 v[66:69], v[178:181], v[220:223], v[66:69]
	v_mfma_f32_16x16x32_bf16 v[82:85], v[178:181], v[212:215], v[82:85]
	v_mfma_f32_16x16x32_bf16 v[82:85], v[170:173], v[208:211], v[82:85]
	v_mfma_f32_16x16x32_bf16 v[98:101], v[170:173], v[190:193], v[98:101]
	v_mfma_f32_16x16x32_bf16 v[98:101], v[178:181], v[204:207], v[98:101]
	v_mfma_f32_16x16x32_bf16 v[114:117], v[178:181], v[186:189], v[114:117]
	v_mfma_f32_16x16x32_bf16 v[114:117], v[170:173], v[182:185], v[114:117]
	s_setprio 0
	s_barrier
	s_add_i32 s0, s0, s20
	v_lshl_add_u64 v[174:175], s[84:85], 0, v[132:133]
	s_mov_b32 m0, s0
	ds_read_b128 v[182:185], v177 offset:16384
	ds_read_b128 v[186:189], v177 offset:17408
	ds_read_b128 v[190:193], v177 offset:18432
	ds_read_b128 v[204:207], v177 offset:19456
	ds_read_b128 v[208:211], v177 offset:20480
	ds_read_b128 v[212:215], v177 offset:21504
	ds_read_b128 v[216:219], v177 offset:22528
	ds_read_b128 v[220:223], v177 offset:23552
	global_load_lds_dwordx4 v[174:175], off
	s_add_i32 m0, s0, 0x2000
	s_add_u32 s94, s84, 0x80000
	v_lshl_add_u64 v[224:225], s[84:85], 0, v[130:131]
	s_addc_u32 s95, s85, 0
	s_add_i32 s0, s1, s20
	global_load_lds_dwordx4 v[224:225], off
	v_lshl_add_u64 v[226:227], s[94:95], 0, v[132:133]
	s_mov_b32 m0, s0
	v_lshl_add_u64 v[228:229], vcc, 0, v[130:131]
	global_load_lds_dwordx4 v[226:227], off
	v_lshl_add_u64 v[226:227], s[94:95], 0, v[130:131]
	s_add_i32 m0, s0, 0x2000
	s_nop 0
	global_load_lds_dwordx4 v[226:227], off
	v_lshl_add_u64 v[226:227], vcc, 0, v[132:133]
	s_mov_b32 m0, s21
	s_nop 0
	global_load_lds_dwordx4 v[226:227], off
	s_mov_b32 m0, s26
	s_nop 0
	global_load_lds_dwordx4 v[228:229], off
	s_waitcnt vmcnt(8)
	s_waitcnt lgkmcnt(0)
	s_barrier
	s_setprio 1
	s_waitcnt lgkmcnt(0)
	v_mfma_f32_16x16x32_bf16 v[62:65], v[146:149], v[182:185], v[62:65]
	v_mfma_f32_16x16x32_bf16 v[62:65], v[150:153], v[186:189], v[62:65]
	v_mfma_f32_16x16x32_bf16 v[46:49], v[150:153], v[204:207], v[46:49]
	v_mfma_f32_16x16x32_bf16 v[46:49], v[146:149], v[190:193], v[46:49]
	v_mfma_f32_16x16x32_bf16 v[30:33], v[146:149], v[208:211], v[30:33]
	v_mfma_f32_16x16x32_bf16 v[30:33], v[150:153], v[212:215], v[30:33]
	v_mfma_f32_16x16x32_bf16 v[14:17], v[150:153], v[220:223], v[14:17]
	v_mfma_f32_16x16x32_bf16 v[14:17], v[146:149], v[216:219], v[14:17]
	v_mfma_f32_16x16x32_bf16 v[10:13], v[154:157], v[216:219], v[10:13]
	v_mfma_f32_16x16x32_bf16 v[10:13], v[158:161], v[220:223], v[10:13]
	v_mfma_f32_16x16x32_bf16 v[26:29], v[158:161], v[212:215], v[26:29]
	v_mfma_f32_16x16x32_bf16 v[26:29], v[154:157], v[208:211], v[26:29]
	v_mfma_f32_16x16x32_bf16 v[42:45], v[154:157], v[190:193], v[42:45]
	v_mfma_f32_16x16x32_bf16 v[42:45], v[158:161], v[204:207], v[42:45]
	v_mfma_f32_16x16x32_bf16 v[58:61], v[158:161], v[186:189], v[58:61]
	v_mfma_f32_16x16x32_bf16 v[58:61], v[154:157], v[182:185], v[58:61]
	v_mfma_f32_16x16x32_bf16 v[54:57], v[162:165], v[182:185], v[54:57]
	v_mfma_f32_16x16x32_bf16 v[54:57], v[166:169], v[186:189], v[54:57]
	v_mfma_f32_16x16x32_bf16 v[38:41], v[166:169], v[204:207], v[38:41]
	v_mfma_f32_16x16x32_bf16 v[38:41], v[162:165], v[190:193], v[38:41]
	v_mfma_f32_16x16x32_bf16 v[22:25], v[162:165], v[208:211], v[22:25]
	v_mfma_f32_16x16x32_bf16 v[22:25], v[166:169], v[212:215], v[22:25]
	v_mfma_f32_16x16x32_bf16 v[6:9], v[166:169], v[220:223], v[6:9]
	v_mfma_f32_16x16x32_bf16 v[6:9], v[162:165], v[216:219], v[6:9]
	v_mfma_f32_16x16x32_bf16 v[2:5], v[170:173], v[216:219], v[2:5]
	v_mfma_f32_16x16x32_bf16 v[2:5], v[178:181], v[220:223], v[2:5]
	v_mfma_f32_16x16x32_bf16 v[18:21], v[178:181], v[212:215], v[18:21]
	v_mfma_f32_16x16x32_bf16 v[18:21], v[170:173], v[208:211], v[18:21]
	v_mfma_f32_16x16x32_bf16 v[34:37], v[170:173], v[190:193], v[34:37]
	v_mfma_f32_16x16x32_bf16 v[34:37], v[178:181], v[204:207], v[34:37]
	v_mfma_f32_16x16x32_bf16 v[50:53], v[178:181], v[186:189], v[50:53]
	v_mfma_f32_16x16x32_bf16 v[50:53], v[170:173], v[182:185], v[50:53]
	s_setprio 0
	s_barrier
	s_add_i32 s0, 0, 0x18000
	s_add_i32 s1, 0, 0x1c000
	v_add_u32_e32 v158, s0, v176
	v_add_u32_e32 v178, s1, v176
	ds_read_b128 v[146:149], v158
	ds_read_b128 v[150:153], v158 offset:1024
	ds_read_b128 v[154:157], v158 offset:2048
	ds_read_b128 v[158:161], v158 offset:3072
	ds_read_b128 v[162:165], v178
	ds_read_b128 v[166:169], v178 offset:1024
	ds_read_b128 v[170:173], v178 offset:2048
	ds_read_b128 v[178:181], v178 offset:3072
	s_add_u32 s94, vcc_lo, 0x80000
	s_addc_u32 s95, vcc_hi, 0
	s_mov_b32 m0, s27
	v_lshl_add_u64 v[230:231], s[94:95], 0, v[132:133]
	ds_read_b128 v[182:185], v177 offset:32768
	ds_read_b128 v[186:189], v177 offset:33792
	ds_read_b128 v[190:193], v177 offset:34816
	ds_read_b128 v[204:207], v177 offset:35840
	ds_read_b128 v[208:211], v177 offset:36864
	ds_read_b128 v[212:215], v177 offset:37888
	ds_read_b128 v[216:219], v177 offset:38912
	ds_read_b128 v[220:223], v177 offset:39936
	global_load_lds_dwordx4 v[230:231], off
	v_lshl_add_u64 v[230:231], s[94:95], 0, v[130:131]
	s_mov_b32 m0, s29
	s_nop 0
	global_load_lds_dwordx4 v[230:231], off
	s_waitcnt vmcnt(8)
	s_waitcnt lgkmcnt(0)
	s_barrier
	s_setprio 1
	s_waitcnt lgkmcnt(0)
	v_mfma_f32_16x16x32_bf16 v[126:129], v[146:149], v[182:185], v[126:129]
	v_mfma_f32_16x16x32_bf16 v[126:129], v[150:153], v[186:189], v[126:129]
	v_mfma_f32_16x16x32_bf16 v[110:113], v[150:153], v[204:207], v[110:113]
	v_mfma_f32_16x16x32_bf16 v[110:113], v[146:149], v[190:193], v[110:113]
	v_mfma_f32_16x16x32_bf16 v[94:97], v[146:149], v[208:211], v[94:97]
	v_mfma_f32_16x16x32_bf16 v[94:97], v[150:153], v[212:215], v[94:97]
	v_mfma_f32_16x16x32_bf16 v[78:81], v[150:153], v[220:223], v[78:81]
	v_mfma_f32_16x16x32_bf16 v[78:81], v[146:149], v[216:219], v[78:81]
	v_mfma_f32_16x16x32_bf16 v[74:77], v[154:157], v[216:219], v[74:77]
	v_mfma_f32_16x16x32_bf16 v[74:77], v[158:161], v[220:223], v[74:77]
	v_mfma_f32_16x16x32_bf16 v[90:93], v[158:161], v[212:215], v[90:93]
	v_mfma_f32_16x16x32_bf16 v[90:93], v[154:157], v[208:211], v[90:93]
	v_mfma_f32_16x16x32_bf16 v[106:109], v[154:157], v[190:193], v[106:109]
	v_mfma_f32_16x16x32_bf16 v[106:109], v[158:161], v[204:207], v[106:109]
	v_mfma_f32_16x16x32_bf16 v[122:125], v[158:161], v[186:189], v[122:125]
	v_mfma_f32_16x16x32_bf16 v[122:125], v[154:157], v[182:185], v[122:125]
	v_mfma_f32_16x16x32_bf16 v[118:121], v[162:165], v[182:185], v[118:121]
	v_mfma_f32_16x16x32_bf16 v[118:121], v[166:169], v[186:189], v[118:121]
	v_mfma_f32_16x16x32_bf16 v[102:105], v[166:169], v[204:207], v[102:105]
	v_mfma_f32_16x16x32_bf16 v[102:105], v[162:165], v[190:193], v[102:105]
	v_mfma_f32_16x16x32_bf16 v[86:89], v[162:165], v[208:211], v[86:89]
	v_mfma_f32_16x16x32_bf16 v[86:89], v[166:169], v[212:215], v[86:89]
	v_mfma_f32_16x16x32_bf16 v[70:73], v[166:169], v[220:223], v[70:73]
	v_mfma_f32_16x16x32_bf16 v[70:73], v[162:165], v[216:219], v[70:73]
	v_mfma_f32_16x16x32_bf16 v[66:69], v[170:173], v[216:219], v[66:69]
	v_mfma_f32_16x16x32_bf16 v[66:69], v[178:181], v[220:223], v[66:69]
	v_mfma_f32_16x16x32_bf16 v[82:85], v[178:181], v[212:215], v[82:85]
	v_mfma_f32_16x16x32_bf16 v[82:85], v[170:173], v[208:211], v[82:85]
	v_mfma_f32_16x16x32_bf16 v[98:101], v[170:173], v[190:193], v[98:101]
	v_mfma_f32_16x16x32_bf16 v[98:101], v[178:181], v[204:207], v[98:101]
	v_mfma_f32_16x16x32_bf16 v[114:117], v[178:181], v[186:189], v[114:117]
	v_mfma_f32_16x16x32_bf16 v[114:117], v[170:173], v[182:185], v[114:117]
	s_setprio 0
	s_barrier
	s_add_i32 s0, s0, s20
	v_lshl_add_u64 v[174:175], v[174:175], 0, s[82:83]
	s_mov_b32 m0, s0
	ds_read_b128 v[182:185], v177 offset:49152
	ds_read_b128 v[186:189], v177 offset:50176
	ds_read_b128 v[190:193], v177 offset:51200
	ds_read_b128 v[204:207], v177 offset:52224
	ds_read_b128 v[208:211], v177 offset:53248
	ds_read_b128 v[212:215], v177 offset:54272
	ds_read_b128 v[216:219], v177 offset:55296
	ds_read_b128 v[220:223], v177 offset:56320
	global_load_lds_dwordx4 v[174:175], off
	s_add_i32 m0, s0, 0x2000
	s_add_u32 s84, s84, 0x80080
	v_lshl_add_u64 v[174:175], v[224:225], 0, s[82:83]
	s_addc_u32 s85, s85, 0
	s_add_i32 s0, s1, s20
	global_load_lds_dwordx4 v[174:175], off
	v_lshl_add_u64 v[174:175], s[84:85], 0, v[132:133]
	s_mov_b32 m0, s0
	s_nop 0
	global_load_lds_dwordx4 v[174:175], off
	v_lshl_add_u64 v[174:175], s[84:85], 0, v[130:131]
	s_add_i32 m0, s0, 0x2000
	s_nop 0
	global_load_lds_dwordx4 v[174:175], off
	v_lshl_add_u64 v[174:175], v[226:227], 0, s[82:83]
	s_mov_b32 m0, s40
	s_nop 0
	global_load_lds_dwordx4 v[174:175], off
	v_lshl_add_u64 v[174:175], v[228:229], 0, s[82:83]
	s_mov_b32 m0, s41
	s_nop 0
	global_load_lds_dwordx4 v[174:175], off
	s_waitcnt vmcnt(8)
	s_waitcnt lgkmcnt(0)
	s_barrier
	s_setprio 1
	s_waitcnt lgkmcnt(0)
	v_mfma_f32_16x16x32_bf16 v[62:65], v[146:149], v[182:185], v[62:65]
	v_mfma_f32_16x16x32_bf16 v[62:65], v[150:153], v[186:189], v[62:65]
	v_mfma_f32_16x16x32_bf16 v[46:49], v[150:153], v[204:207], v[46:49]
	v_mfma_f32_16x16x32_bf16 v[46:49], v[146:149], v[190:193], v[46:49]
	v_mfma_f32_16x16x32_bf16 v[30:33], v[146:149], v[208:211], v[30:33]
	v_mfma_f32_16x16x32_bf16 v[30:33], v[150:153], v[212:215], v[30:33]
	v_mfma_f32_16x16x32_bf16 v[14:17], v[150:153], v[220:223], v[14:17]
	v_mfma_f32_16x16x32_bf16 v[14:17], v[146:149], v[216:219], v[14:17]
	v_mfma_f32_16x16x32_bf16 v[10:13], v[154:157], v[216:219], v[10:13]
	v_mfma_f32_16x16x32_bf16 v[10:13], v[158:161], v[220:223], v[10:13]
	v_mfma_f32_16x16x32_bf16 v[26:29], v[158:161], v[212:215], v[26:29]
	v_mfma_f32_16x16x32_bf16 v[26:29], v[154:157], v[208:211], v[26:29]
	v_mfma_f32_16x16x32_bf16 v[42:45], v[154:157], v[190:193], v[42:45]
	v_mfma_f32_16x16x32_bf16 v[42:45], v[158:161], v[204:207], v[42:45]
	v_mfma_f32_16x16x32_bf16 v[58:61], v[158:161], v[186:189], v[58:61]
	v_mfma_f32_16x16x32_bf16 v[58:61], v[154:157], v[182:185], v[58:61]
	v_mfma_f32_16x16x32_bf16 v[54:57], v[162:165], v[182:185], v[54:57]
	v_mfma_f32_16x16x32_bf16 v[54:57], v[166:169], v[186:189], v[54:57]
	v_mfma_f32_16x16x32_bf16 v[38:41], v[166:169], v[204:207], v[38:41]
	v_mfma_f32_16x16x32_bf16 v[38:41], v[162:165], v[190:193], v[38:41]
	v_mfma_f32_16x16x32_bf16 v[22:25], v[162:165], v[208:211], v[22:25]
	v_mfma_f32_16x16x32_bf16 v[22:25], v[166:169], v[212:215], v[22:25]
	v_mfma_f32_16x16x32_bf16 v[6:9], v[166:169], v[220:223], v[6:9]
	v_mfma_f32_16x16x32_bf16 v[6:9], v[162:165], v[216:219], v[6:9]
	v_mfma_f32_16x16x32_bf16 v[2:5], v[170:173], v[216:219], v[2:5]
	v_mfma_f32_16x16x32_bf16 v[2:5], v[178:181], v[220:223], v[2:5]
	v_mfma_f32_16x16x32_bf16 v[18:21], v[178:181], v[212:215], v[18:21]
	v_mfma_f32_16x16x32_bf16 v[18:21], v[170:173], v[208:211], v[18:21]
	v_mfma_f32_16x16x32_bf16 v[34:37], v[170:173], v[190:193], v[34:37]
	v_mfma_f32_16x16x32_bf16 v[34:37], v[178:181], v[204:207], v[34:37]
	v_mfma_f32_16x16x32_bf16 v[50:53], v[178:181], v[186:189], v[50:53]
	v_mfma_f32_16x16x32_bf16 v[50:53], v[170:173], v[182:185], v[50:53]
	s_setprio 0
	s_barrier
	s_add_i32 s65, s65, 2
	s_add_u32 s76, s76, 0x100
	s_addc_u32 s77, s77, 0
	s_add_u32 s51, s51, 0x100
	s_addc_u32 s58, s58, 0
	s_cmp_gt_u32 s65, 29
	s_cbranch_scc1 .LBB0_264

.LBB0_285:
	s_add_u32 s0, s76, 0xfff80080
	s_addc_u32 s1, s77, -1
	s_and_b64 s[70:71], s[70:71], exec
	s_cselect_b32 vcc_hi, s21, s1
	s_cselect_b32 vcc_lo, s22, s0
	s_cselect_b32 s71, s23, s41
	s_cselect_b32 s70, s39, s7
	s_add_i32 s0, 0, 0x10000
	s_add_i32 s1, 0, 0x14000
	v_add_u32_e32 v146, s0, v1
	v_add_u32_e32 v174, s1, v1
	ds_read_b128 v[134:137], v146
	ds_read_b128 v[138:141], v146 offset:1024
	ds_read_b128 v[142:145], v146 offset:2048
	ds_read_b128 v[146:149], v146 offset:3072
	ds_read_b128 v[150:153], v174
	ds_read_b128 v[154:157], v174 offset:1024
	ds_read_b128 v[158:161], v174 offset:2048
	ds_read_b128 v[174:177], v174 offset:3072
	v_lshl_add_u64 v[220:221], s[76:77], 0, v[170:171]
	s_add_i32 m0, s67, 0xc000
	ds_read_b128 v[178:181], v222
	ds_read_b128 v[182:185], v222 offset:1024
	ds_read_b128 v[186:189], v222 offset:2048
	ds_read_b128 v[190:193], v222 offset:3072
	ds_read_b128 v[204:207], v222 offset:4096
	ds_read_b128 v[208:211], v222 offset:5120
	ds_read_b128 v[212:215], v222 offset:6144
	ds_read_b128 v[216:219], v222 offset:7168
	global_load_lds_dwordx4 v[220:221], off
	v_lshl_add_u64 v[220:221], s[76:77], 0, v[172:173]
	s_add_i32 m0, s67, 0xe000
	s_nop 0
	global_load_lds_dwordx4 v[220:221], off
	s_waitcnt vmcnt(8)
	s_waitcnt lgkmcnt(0)
	s_barrier
	s_setprio 1
	s_waitcnt lgkmcnt(0)
	v_mfma_f32_16x16x32_bf16 v[126:129], v[134:137], v[178:181], v[126:129]
	v_mfma_f32_16x16x32_bf16 v[126:129], v[138:141], v[182:185], v[126:129]
	v_mfma_f32_16x16x32_bf16 v[110:113], v[138:141], v[190:193], v[110:113]
	v_mfma_f32_16x16x32_bf16 v[110:113], v[134:137], v[186:189], v[110:113]
	v_mfma_f32_16x16x32_bf16 v[94:97], v[134:137], v[204:207], v[94:97]
	v_mfma_f32_16x16x32_bf16 v[94:97], v[138:141], v[208:211], v[94:97]
	v_mfma_f32_16x16x32_bf16 v[78:81], v[138:141], v[216:219], v[78:81]
	v_mfma_f32_16x16x32_bf16 v[78:81], v[134:137], v[212:215], v[78:81]
	v_mfma_f32_16x16x32_bf16 v[74:77], v[142:145], v[212:215], v[74:77]
	v_mfma_f32_16x16x32_bf16 v[74:77], v[146:149], v[216:219], v[74:77]
	v_mfma_f32_16x16x32_bf16 v[90:93], v[146:149], v[208:211], v[90:93]
	v_mfma_f32_16x16x32_bf16 v[90:93], v[142:145], v[204:207], v[90:93]
	v_mfma_f32_16x16x32_bf16 v[106:109], v[142:145], v[186:189], v[106:109]
	v_mfma_f32_16x16x32_bf16 v[106:109], v[146:149], v[190:193], v[106:109]
	v_mfma_f32_16x16x32_bf16 v[122:125], v[146:149], v[182:185], v[122:125]
	v_mfma_f32_16x16x32_bf16 v[122:125], v[142:145], v[178:181], v[122:125]
	v_mfma_f32_16x16x32_bf16 v[118:121], v[150:153], v[178:181], v[118:121]
	v_mfma_f32_16x16x32_bf16 v[118:121], v[154:157], v[182:185], v[118:121]
	v_mfma_f32_16x16x32_bf16 v[102:105], v[154:157], v[190:193], v[102:105]
	v_mfma_f32_16x16x32_bf16 v[102:105], v[150:153], v[186:189], v[102:105]
	v_mfma_f32_16x16x32_bf16 v[86:89], v[150:153], v[204:207], v[86:89]
	v_mfma_f32_16x16x32_bf16 v[86:89], v[154:157], v[208:211], v[86:89]
	v_mfma_f32_16x16x32_bf16 v[70:73], v[154:157], v[216:219], v[70:73]
	v_mfma_f32_16x16x32_bf16 v[70:73], v[150:153], v[212:215], v[70:73]
	v_mfma_f32_16x16x32_bf16 v[66:69], v[158:161], v[212:215], v[66:69]
	v_mfma_f32_16x16x32_bf16 v[66:69], v[174:177], v[216:219], v[66:69]
	v_mfma_f32_16x16x32_bf16 v[82:85], v[174:177], v[208:211], v[82:85]
	v_mfma_f32_16x16x32_bf16 v[82:85], v[158:161], v[204:207], v[82:85]
	v_mfma_f32_16x16x32_bf16 v[98:101], v[158:161], v[186:189], v[98:101]
	v_mfma_f32_16x16x32_bf16 v[98:101], v[174:177], v[190:193], v[98:101]
	v_mfma_f32_16x16x32_bf16 v[114:117], v[174:177], v[182:185], v[114:117]
	v_mfma_f32_16x16x32_bf16 v[114:117], v[158:161], v[178:181], v[114:117]
	s_setprio 0
	s_barrier
	s_add_i32 s0, s0, s54
	v_lshl_add_u64 v[220:221], s[70:71], 0, v[164:165]
	s_mov_b32 m0, s0
	ds_read_b128 v[178:181], v222 offset:16384
	ds_read_b128 v[182:185], v222 offset:17408
	ds_read_b128 v[186:189], v222 offset:18432
	ds_read_b128 v[190:193], v222 offset:19456
	ds_read_b128 v[204:207], v222 offset:20480
	ds_read_b128 v[208:211], v222 offset:21504
	ds_read_b128 v[212:215], v222 offset:22528
	ds_read_b128 v[216:219], v222 offset:23552
	global_load_lds_dwordx4 v[220:221], off
	s_add_i32 m0, s0, 0x2000
	s_add_u32 s44, s70, 0x80000
	v_lshl_add_u64 v[224:225], s[70:71], 0, v[162:163]
	s_addc_u32 s45, s71, 0
	s_add_i32 s0, s1, s54
	global_load_lds_dwordx4 v[224:225], off
	v_lshl_add_u64 v[226:227], s[44:45], 0, v[164:165]
	s_mov_b32 m0, s0
	v_lshl_add_u64 v[228:229], vcc, 0, v[162:163]
	global_load_lds_dwordx4 v[226:227], off
	v_lshl_add_u64 v[226:227], s[44:45], 0, v[162:163]
	s_add_i32 m0, s0, 0x2000
	s_nop 0
	global_load_lds_dwordx4 v[226:227], off
	v_lshl_add_u64 v[226:227], vcc, 0, v[164:165]
	s_mov_b32 m0, s67
	s_nop 0
	global_load_lds_dwordx4 v[226:227], off
	s_mov_b32 m0, s68
	s_nop 0
	global_load_lds_dwordx4 v[228:229], off
	s_waitcnt vmcnt(8)
	s_waitcnt lgkmcnt(0)
	s_barrier
	s_setprio 1
	s_waitcnt lgkmcnt(0)
	v_mfma_f32_16x16x32_bf16 v[62:65], v[134:137], v[178:181], v[62:65]
	v_mfma_f32_16x16x32_bf16 v[62:65], v[138:141], v[182:185], v[62:65]
	v_mfma_f32_16x16x32_bf16 v[46:49], v[138:141], v[190:193], v[46:49]
	v_mfma_f32_16x16x32_bf16 v[46:49], v[134:137], v[186:189], v[46:49]
	v_mfma_f32_16x16x32_bf16 v[30:33], v[134:137], v[204:207], v[30:33]
	v_mfma_f32_16x16x32_bf16 v[30:33], v[138:141], v[208:211], v[30:33]
	v_mfma_f32_16x16x32_bf16 v[14:17], v[138:141], v[216:219], v[14:17]
	v_mfma_f32_16x16x32_bf16 v[14:17], v[134:137], v[212:215], v[14:17]
	v_mfma_f32_16x16x32_bf16 v[10:13], v[142:145], v[212:215], v[10:13]
	v_mfma_f32_16x16x32_bf16 v[10:13], v[146:149], v[216:219], v[10:13]
	v_mfma_f32_16x16x32_bf16 v[26:29], v[146:149], v[208:211], v[26:29]
	v_mfma_f32_16x16x32_bf16 v[26:29], v[142:145], v[204:207], v[26:29]
	v_mfma_f32_16x16x32_bf16 v[42:45], v[142:145], v[186:189], v[42:45]
	v_mfma_f32_16x16x32_bf16 v[42:45], v[146:149], v[190:193], v[42:45]
	v_mfma_f32_16x16x32_bf16 v[58:61], v[146:149], v[182:185], v[58:61]
	v_mfma_f32_16x16x32_bf16 v[58:61], v[142:145], v[178:181], v[58:61]
	v_mfma_f32_16x16x32_bf16 v[54:57], v[150:153], v[178:181], v[54:57]
	v_mfma_f32_16x16x32_bf16 v[54:57], v[154:157], v[182:185], v[54:57]
	v_mfma_f32_16x16x32_bf16 v[38:41], v[154:157], v[190:193], v[38:41]
	v_mfma_f32_16x16x32_bf16 v[38:41], v[150:153], v[186:189], v[38:41]
	v_mfma_f32_16x16x32_bf16 v[22:25], v[150:153], v[204:207], v[22:25]
	v_mfma_f32_16x16x32_bf16 v[22:25], v[154:157], v[208:211], v[22:25]
	v_mfma_f32_16x16x32_bf16 v[6:9], v[154:157], v[216:219], v[6:9]
	v_mfma_f32_16x16x32_bf16 v[6:9], v[150:153], v[212:215], v[6:9]
	v_mfma_f32_16x16x32_bf16 v[2:5], v[158:161], v[212:215], v[2:5]
	v_mfma_f32_16x16x32_bf16 v[2:5], v[174:177], v[216:219], v[2:5]
	v_mfma_f32_16x16x32_bf16 v[18:21], v[174:177], v[208:211], v[18:21]
	v_mfma_f32_16x16x32_bf16 v[18:21], v[158:161], v[204:207], v[18:21]
	v_mfma_f32_16x16x32_bf16 v[34:37], v[158:161], v[186:189], v[34:37]
	v_mfma_f32_16x16x32_bf16 v[34:37], v[174:177], v[190:193], v[34:37]
	v_mfma_f32_16x16x32_bf16 v[50:53], v[174:177], v[182:185], v[50:53]
	v_mfma_f32_16x16x32_bf16 v[50:53], v[158:161], v[178:181], v[50:53]
	s_setprio 0
	s_barrier
	s_add_i32 s0, 0, 0x18000
	s_add_i32 s1, 0, 0x1c000
	v_add_u32_e32 v146, s0, v1
	v_add_u32_e32 v174, s1, v1
	ds_read_b128 v[134:137], v146
	ds_read_b128 v[138:141], v146 offset:1024
	ds_read_b128 v[142:145], v146 offset:2048
	ds_read_b128 v[146:149], v146 offset:3072
	ds_read_b128 v[150:153], v174
	ds_read_b128 v[154:157], v174 offset:1024
	ds_read_b128 v[158:161], v174 offset:2048
	ds_read_b128 v[174:177], v174 offset:3072
	s_add_u32 s44, vcc_lo, 0x80000
	s_addc_u32 s45, vcc_hi, 0
	s_mov_b32 m0, s8
	v_lshl_add_u64 v[230:231], s[44:45], 0, v[164:165]
	ds_read_b128 v[178:181], v222 offset:32768
	ds_read_b128 v[182:185], v222 offset:33792
	ds_read_b128 v[186:189], v222 offset:34816
	ds_read_b128 v[190:193], v222 offset:35840
	ds_read_b128 v[204:207], v222 offset:36864
	ds_read_b128 v[208:211], v222 offset:37888
	ds_read_b128 v[212:215], v222 offset:38912
	ds_read_b128 v[216:219], v222 offset:39936
	global_load_lds_dwordx4 v[230:231], off
	v_lshl_add_u64 v[230:231], s[44:45], 0, v[162:163]
	s_mov_b32 m0, s9
	s_nop 0
	global_load_lds_dwordx4 v[230:231], off
	s_waitcnt vmcnt(8)
	s_waitcnt lgkmcnt(0)
	s_barrier
	s_setprio 1
	s_waitcnt lgkmcnt(0)
	v_mfma_f32_16x16x32_bf16 v[126:129], v[134:137], v[178:181], v[126:129]
	v_mfma_f32_16x16x32_bf16 v[126:129], v[138:141], v[182:185], v[126:129]
	v_mfma_f32_16x16x32_bf16 v[110:113], v[138:141], v[190:193], v[110:113]
	v_mfma_f32_16x16x32_bf16 v[110:113], v[134:137], v[186:189], v[110:113]
	v_mfma_f32_16x16x32_bf16 v[94:97], v[134:137], v[204:207], v[94:97]
	v_mfma_f32_16x16x32_bf16 v[94:97], v[138:141], v[208:211], v[94:97]
	v_mfma_f32_16x16x32_bf16 v[78:81], v[138:141], v[216:219], v[78:81]
	v_mfma_f32_16x16x32_bf16 v[78:81], v[134:137], v[212:215], v[78:81]
	v_mfma_f32_16x16x32_bf16 v[74:77], v[142:145], v[212:215], v[74:77]
	v_mfma_f32_16x16x32_bf16 v[74:77], v[146:149], v[216:219], v[74:77]
	v_mfma_f32_16x16x32_bf16 v[90:93], v[146:149], v[208:211], v[90:93]
	v_mfma_f32_16x16x32_bf16 v[90:93], v[142:145], v[204:207], v[90:93]
	v_mfma_f32_16x16x32_bf16 v[106:109], v[142:145], v[186:189], v[106:109]
	v_mfma_f32_16x16x32_bf16 v[106:109], v[146:149], v[190:193], v[106:109]
	v_mfma_f32_16x16x32_bf16 v[122:125], v[146:149], v[182:185], v[122:125]
	v_mfma_f32_16x16x32_bf16 v[122:125], v[142:145], v[178:181], v[122:125]
	v_mfma_f32_16x16x32_bf16 v[118:121], v[150:153], v[178:181], v[118:121]
	v_mfma_f32_16x16x32_bf16 v[118:121], v[154:157], v[182:185], v[118:121]
	v_mfma_f32_16x16x32_bf16 v[102:105], v[154:157], v[190:193], v[102:105]
	v_mfma_f32_16x16x32_bf16 v[102:105], v[150:153], v[186:189], v[102:105]
	v_mfma_f32_16x16x32_bf16 v[86:89], v[150:153], v[204:207], v[86:89]
	v_mfma_f32_16x16x32_bf16 v[86:89], v[154:157], v[208:211], v[86:89]
	v_mfma_f32_16x16x32_bf16 v[70:73], v[154:157], v[216:219], v[70:73]
	v_mfma_f32_16x16x32_bf16 v[70:73], v[150:153], v[212:215], v[70:73]
	v_mfma_f32_16x16x32_bf16 v[66:69], v[158:161], v[212:215], v[66:69]
	v_mfma_f32_16x16x32_bf16 v[66:69], v[174:177], v[216:219], v[66:69]
	v_mfma_f32_16x16x32_bf16 v[82:85], v[174:177], v[208:211], v[82:85]
	v_mfma_f32_16x16x32_bf16 v[82:85], v[158:161], v[204:207], v[82:85]
	v_mfma_f32_16x16x32_bf16 v[98:101], v[158:161], v[186:189], v[98:101]
	v_mfma_f32_16x16x32_bf16 v[98:101], v[174:177], v[190:193], v[98:101]
	v_mfma_f32_16x16x32_bf16 v[114:117], v[174:177], v[182:185], v[114:117]
	v_mfma_f32_16x16x32_bf16 v[114:117], v[158:161], v[178:181], v[114:117]
	s_setprio 0
	s_barrier
	s_add_i32 s0, s0, s54
	v_lshl_add_u64 v[220:221], v[220:221], 0, s[82:83]
	s_mov_b32 m0, s0
	ds_read_b128 v[178:181], v222 offset:49152
	ds_read_b128 v[182:185], v222 offset:50176
	ds_read_b128 v[186:189], v222 offset:51200
	ds_read_b128 v[190:193], v222 offset:52224
	ds_read_b128 v[204:207], v222 offset:53248
	ds_read_b128 v[208:211], v222 offset:54272
	ds_read_b128 v[212:215], v222 offset:55296
	ds_read_b128 v[216:219], v222 offset:56320
	global_load_lds_dwordx4 v[220:221], off
	s_add_i32 m0, s0, 0x2000
	s_add_u32 s44, s70, 0x80080
	v_lshl_add_u64 v[220:221], v[224:225], 0, s[82:83]
	s_addc_u32 s45, s71, 0
	s_add_i32 s0, s1, s54
	global_load_lds_dwordx4 v[220:221], off
	v_lshl_add_u64 v[220:221], s[44:45], 0, v[164:165]
	s_mov_b32 m0, s0
	s_nop 0
	global_load_lds_dwordx4 v[220:221], off
	v_lshl_add_u64 v[220:221], s[44:45], 0, v[162:163]
	s_add_i32 m0, s0, 0x2000
	s_nop 0
	global_load_lds_dwordx4 v[220:221], off
	v_lshl_add_u64 v[220:221], v[226:227], 0, s[82:83]
	s_mov_b32 m0, s27
	s_nop 0
	global_load_lds_dwordx4 v[220:221], off
	v_lshl_add_u64 v[220:221], v[228:229], 0, s[82:83]
	s_mov_b32 m0, s26
	s_nop 0
	global_load_lds_dwordx4 v[220:221], off
	s_waitcnt vmcnt(8)
	s_waitcnt lgkmcnt(0)
	s_barrier
	s_setprio 1
	s_waitcnt lgkmcnt(0)
	v_mfma_f32_16x16x32_bf16 v[62:65], v[134:137], v[178:181], v[62:65]
	v_mfma_f32_16x16x32_bf16 v[62:65], v[138:141], v[182:185], v[62:65]
	v_mfma_f32_16x16x32_bf16 v[46:49], v[138:141], v[190:193], v[46:49]
	v_mfma_f32_16x16x32_bf16 v[46:49], v[134:137], v[186:189], v[46:49]
	v_mfma_f32_16x16x32_bf16 v[30:33], v[134:137], v[204:207], v[30:33]
	v_mfma_f32_16x16x32_bf16 v[30:33], v[138:141], v[208:211], v[30:33]
	v_mfma_f32_16x16x32_bf16 v[14:17], v[138:141], v[216:219], v[14:17]
	v_mfma_f32_16x16x32_bf16 v[14:17], v[134:137], v[212:215], v[14:17]
	v_mfma_f32_16x16x32_bf16 v[10:13], v[142:145], v[212:215], v[10:13]
	v_mfma_f32_16x16x32_bf16 v[10:13], v[146:149], v[216:219], v[10:13]
	v_mfma_f32_16x16x32_bf16 v[26:29], v[146:149], v[208:211], v[26:29]
	v_mfma_f32_16x16x32_bf16 v[26:29], v[142:145], v[204:207], v[26:29]
	v_mfma_f32_16x16x32_bf16 v[42:45], v[142:145], v[186:189], v[42:45]
	v_mfma_f32_16x16x32_bf16 v[42:45], v[146:149], v[190:193], v[42:45]
	v_mfma_f32_16x16x32_bf16 v[58:61], v[146:149], v[182:185], v[58:61]
	v_mfma_f32_16x16x32_bf16 v[58:61], v[142:145], v[178:181], v[58:61]
	v_mfma_f32_16x16x32_bf16 v[54:57], v[150:153], v[178:181], v[54:57]
	v_mfma_f32_16x16x32_bf16 v[54:57], v[154:157], v[182:185], v[54:57]
	v_mfma_f32_16x16x32_bf16 v[38:41], v[154:157], v[190:193], v[38:41]
	v_mfma_f32_16x16x32_bf16 v[38:41], v[150:153], v[186:189], v[38:41]
	v_mfma_f32_16x16x32_bf16 v[22:25], v[150:153], v[204:207], v[22:25]
	v_mfma_f32_16x16x32_bf16 v[22:25], v[154:157], v[208:211], v[22:25]
	v_mfma_f32_16x16x32_bf16 v[6:9], v[154:157], v[216:219], v[6:9]
	v_mfma_f32_16x16x32_bf16 v[6:9], v[150:153], v[212:215], v[6:9]
	v_mfma_f32_16x16x32_bf16 v[2:5], v[158:161], v[212:215], v[2:5]
	v_mfma_f32_16x16x32_bf16 v[2:5], v[174:177], v[216:219], v[2:5]
	v_mfma_f32_16x16x32_bf16 v[18:21], v[174:177], v[208:211], v[18:21]
	v_mfma_f32_16x16x32_bf16 v[18:21], v[158:161], v[204:207], v[18:21]
	v_mfma_f32_16x16x32_bf16 v[34:37], v[158:161], v[186:189], v[34:37]
	v_mfma_f32_16x16x32_bf16 v[34:37], v[174:177], v[190:193], v[34:37]
	v_mfma_f32_16x16x32_bf16 v[50:53], v[174:177], v[182:185], v[50:53]
	v_mfma_f32_16x16x32_bf16 v[50:53], v[158:161], v[178:181], v[50:53]
	s_setprio 0
	s_barrier
	s_add_i32 s43, s43, 2
	s_add_u32 s76, s76, 0x100
	s_addc_u32 s77, s77, 0
	s_add_u32 s7, s7, 0x100
	s_addc_u32 s41, s41, 0
	s_cmp_gt_u32 s43, 29
	s_cbranch_scc1 .LBB0_288

.LBB0_509:
	s_add_u32 s90, s76, 0x100
	s_addc_u32 s91, s77, 0
	s_and_b64 s[0:1], s[70:71], exec
	s_cselect_b32 vcc_hi, s22, s91
	s_cselect_b32 vcc_lo, s23, s90
	s_cselect_b32 s71, s41, s53
	s_cselect_b32 s70, s44, s51
	s_add_i32 s0, 0, 0x10000
	s_add_i32 s18, 0, 0x14000
	v_add_u32_e32 v114, s0, v1
	v_add_u32_e32 v154, s18, v1
	ds_read_b128 v[78:81], v114
	ds_read_b128 v[90:93], v114 offset:1024
	ds_read_b128 v[102:105], v114 offset:2048
	ds_read_b128 v[114:117], v114 offset:3072
	ds_read_b128 v[126:129], v154
	ds_read_b128 v[134:137], v154 offset:1024
	ds_read_b128 v[142:145], v154 offset:2048
	ds_read_b128 v[154:157], v154 offset:3072
	v_lshl_add_u64 v[218:219], s[76:77], 0, v[210:211]
	s_add_i32 m0, s29, 0xc000
	ds_read_b128 v[158:161], v237
	ds_read_b128 v[162:165], v237 offset:1024
	ds_read_b128 v[166:169], v237 offset:2048
	ds_read_b128 v[178:181], v237 offset:3072
	ds_read_b128 v[182:185], v237 offset:4096
	ds_read_b128 v[186:189], v237 offset:5120
	ds_read_b128 v[190:193], v237 offset:6144
	ds_read_b128 v[214:217], v237 offset:7168
	global_load_lds_dwordx4 v[218:219], off
	v_lshl_add_u64 v[218:219], s[76:77], 0, v[212:213]
	s_add_i32 m0, s29, 0xe000
	s_nop 0
	global_load_lds_dwordx4 v[218:219], off
	s_waitcnt vmcnt(8)
	s_waitcnt lgkmcnt(0)
	s_barrier
	s_setprio 1
	s_waitcnt lgkmcnt(0)
	v_mfma_f32_16x16x32_bf16 v[174:177], v[78:81], v[158:161], v[174:177]
	v_mfma_f32_16x16x32_bf16 v[174:177], v[90:93], v[162:165], v[174:177]
	v_mfma_f32_16x16x32_bf16 v[138:141], v[90:93], v[178:181], v[138:141]
	v_mfma_f32_16x16x32_bf16 v[138:141], v[78:81], v[166:169], v[138:141]
	v_mfma_f32_16x16x32_bf16 v[110:113], v[78:81], v[182:185], v[110:113]
	v_mfma_f32_16x16x32_bf16 v[110:113], v[90:93], v[186:189], v[110:113]
	v_mfma_f32_16x16x32_bf16 v[86:89], v[90:93], v[214:217], v[86:89]
	v_mfma_f32_16x16x32_bf16 v[86:89], v[78:81], v[190:193], v[86:89]
	v_mfma_f32_16x16x32_bf16 v[82:85], v[102:105], v[190:193], v[82:85]
	v_mfma_f32_16x16x32_bf16 v[82:85], v[114:117], v[214:217], v[82:85]
	v_mfma_f32_16x16x32_bf16 v[106:109], v[114:117], v[186:189], v[106:109]
	v_mfma_f32_16x16x32_bf16 v[106:109], v[102:105], v[182:185], v[106:109]
	v_mfma_f32_16x16x32_bf16 v[130:133], v[102:105], v[166:169], v[130:133]
	v_mfma_f32_16x16x32_bf16 v[130:133], v[114:117], v[178:181], v[130:133]
	v_mfma_f32_16x16x32_bf16 v[170:173], v[114:117], v[162:165], v[170:173]
	v_mfma_f32_16x16x32_bf16 v[170:173], v[102:105], v[158:161], v[170:173]
	v_mfma_f32_16x16x32_bf16 v[150:153], v[126:129], v[158:161], v[150:153]
	v_mfma_f32_16x16x32_bf16 v[150:153], v[134:137], v[162:165], v[150:153]
	v_mfma_f32_16x16x32_bf16 v[122:125], v[134:137], v[178:181], v[122:125]
	v_mfma_f32_16x16x32_bf16 v[122:125], v[126:129], v[166:169], v[122:125]
	v_mfma_f32_16x16x32_bf16 v[98:101], v[126:129], v[182:185], v[98:101]
	v_mfma_f32_16x16x32_bf16 v[98:101], v[134:137], v[186:189], v[98:101]
	v_mfma_f32_16x16x32_bf16 v[74:77], v[134:137], v[214:217], v[74:77]
	v_mfma_f32_16x16x32_bf16 v[74:77], v[126:129], v[190:193], v[74:77]
	v_mfma_f32_16x16x32_bf16 v[66:69], v[142:145], v[190:193], v[66:69]
	v_mfma_f32_16x16x32_bf16 v[66:69], v[154:157], v[214:217], v[66:69]
	v_mfma_f32_16x16x32_bf16 v[94:97], v[154:157], v[186:189], v[94:97]
	v_mfma_f32_16x16x32_bf16 v[94:97], v[142:145], v[182:185], v[94:97]
	v_mfma_f32_16x16x32_bf16 v[118:121], v[142:145], v[166:169], v[118:121]
	v_mfma_f32_16x16x32_bf16 v[118:121], v[154:157], v[178:181], v[118:121]
	v_mfma_f32_16x16x32_bf16 v[146:149], v[154:157], v[162:165], v[146:149]
	v_mfma_f32_16x16x32_bf16 v[146:149], v[142:145], v[158:161], v[146:149]
	s_setprio 0
	s_barrier
	s_add_i32 s0, s0, s28
	v_lshl_add_u64 v[218:219], s[70:71], 0, v[194:195]
	s_mov_b32 m0, s0
	ds_read_b128 v[158:161], v237 offset:16384
	ds_read_b128 v[162:165], v237 offset:17408
	ds_read_b128 v[166:169], v237 offset:18432
	ds_read_b128 v[178:181], v237 offset:19456
	ds_read_b128 v[182:185], v237 offset:20480
	ds_read_b128 v[186:189], v237 offset:21504
	ds_read_b128 v[190:193], v237 offset:22528
	ds_read_b128 v[214:217], v237 offset:23552
	global_load_lds_dwordx4 v[218:219], off
	s_add_i32 m0, s0, 0x2000
	s_add_u32 s0, s70, 0x80000
	v_lshl_add_u64 v[220:221], s[70:71], 0, v[204:205]
	s_addc_u32 s1, s71, 0
	s_add_i32 s18, s18, s28
	global_load_lds_dwordx4 v[220:221], off
	v_lshl_add_u64 v[222:223], s[0:1], 0, v[194:195]
	s_mov_b32 m0, s18
	v_lshl_add_u64 v[224:225], vcc, 0, v[204:205]
	global_load_lds_dwordx4 v[222:223], off
	v_lshl_add_u64 v[222:223], s[0:1], 0, v[204:205]
	s_add_i32 m0, s18, 0x2000
	s_nop 0
	global_load_lds_dwordx4 v[222:223], off
	v_lshl_add_u64 v[222:223], vcc, 0, v[194:195]
	s_mov_b32 m0, s29
	s_nop 0
	global_load_lds_dwordx4 v[222:223], off
	s_mov_b32 m0, s31
	s_nop 0
	global_load_lds_dwordx4 v[224:225], off
	s_waitcnt vmcnt(8)
	s_waitcnt lgkmcnt(0)
	s_barrier
	s_setprio 1
	s_waitcnt lgkmcnt(0)
	v_mfma_f32_16x16x32_bf16 v[62:65], v[78:81], v[158:161], v[62:65]
	v_mfma_f32_16x16x32_bf16 v[62:65], v[90:93], v[162:165], v[62:65]
	v_mfma_f32_16x16x32_bf16 v[46:49], v[90:93], v[178:181], v[46:49]
	v_mfma_f32_16x16x32_bf16 v[46:49], v[78:81], v[166:169], v[46:49]
	v_mfma_f32_16x16x32_bf16 v[30:33], v[78:81], v[182:185], v[30:33]
	v_mfma_f32_16x16x32_bf16 v[30:33], v[90:93], v[186:189], v[30:33]
	v_mfma_f32_16x16x32_bf16 v[14:17], v[90:93], v[214:217], v[14:17]
	v_mfma_f32_16x16x32_bf16 v[14:17], v[78:81], v[190:193], v[14:17]
	v_mfma_f32_16x16x32_bf16 v[10:13], v[102:105], v[190:193], v[10:13]
	v_mfma_f32_16x16x32_bf16 v[10:13], v[114:117], v[214:217], v[10:13]
	v_mfma_f32_16x16x32_bf16 v[26:29], v[114:117], v[186:189], v[26:29]
	v_mfma_f32_16x16x32_bf16 v[26:29], v[102:105], v[182:185], v[26:29]
	v_mfma_f32_16x16x32_bf16 v[42:45], v[102:105], v[166:169], v[42:45]
	v_mfma_f32_16x16x32_bf16 v[42:45], v[114:117], v[178:181], v[42:45]
	v_mfma_f32_16x16x32_bf16 v[58:61], v[114:117], v[162:165], v[58:61]
	v_mfma_f32_16x16x32_bf16 v[58:61], v[102:105], v[158:161], v[58:61]
	v_mfma_f32_16x16x32_bf16 v[54:57], v[126:129], v[158:161], v[54:57]
	v_mfma_f32_16x16x32_bf16 v[54:57], v[134:137], v[162:165], v[54:57]
	v_mfma_f32_16x16x32_bf16 v[38:41], v[134:137], v[178:181], v[38:41]
	v_mfma_f32_16x16x32_bf16 v[38:41], v[126:129], v[166:169], v[38:41]
	v_mfma_f32_16x16x32_bf16 v[22:25], v[126:129], v[182:185], v[22:25]
	v_mfma_f32_16x16x32_bf16 v[22:25], v[134:137], v[186:189], v[22:25]
	v_mfma_f32_16x16x32_bf16 v[6:9], v[134:137], v[214:217], v[6:9]
	v_mfma_f32_16x16x32_bf16 v[6:9], v[126:129], v[190:193], v[6:9]
	v_mfma_f32_16x16x32_bf16 v[2:5], v[142:145], v[190:193], v[2:5]
	v_mfma_f32_16x16x32_bf16 v[2:5], v[154:157], v[214:217], v[2:5]
	v_mfma_f32_16x16x32_bf16 v[18:21], v[154:157], v[186:189], v[18:21]
	v_mfma_f32_16x16x32_bf16 v[18:21], v[142:145], v[182:185], v[18:21]
	v_mfma_f32_16x16x32_bf16 v[34:37], v[142:145], v[166:169], v[34:37]
	v_mfma_f32_16x16x32_bf16 v[34:37], v[154:157], v[178:181], v[34:37]
	v_mfma_f32_16x16x32_bf16 v[50:53], v[154:157], v[162:165], v[50:53]
	v_mfma_f32_16x16x32_bf16 v[50:53], v[142:145], v[158:161], v[50:53]
	s_setprio 0
	s_barrier
	s_add_i32 s18, 0, 0x18000
	s_add_i32 s19, 0, 0x1c000
	v_add_u32_e32 v114, s18, v1
	v_add_u32_e32 v154, s19, v1
	ds_read_b128 v[78:81], v114
	ds_read_b128 v[90:93], v114 offset:1024
	ds_read_b128 v[102:105], v114 offset:2048
	ds_read_b128 v[114:117], v114 offset:3072
	ds_read_b128 v[126:129], v154
	ds_read_b128 v[134:137], v154 offset:1024
	ds_read_b128 v[142:145], v154 offset:2048
	ds_read_b128 v[154:157], v154 offset:3072
	s_add_u32 s0, vcc_lo, 0x80000
	s_addc_u32 s1, vcc_hi, 0
	s_mov_b32 m0, s33
	v_lshl_add_u64 v[226:227], s[0:1], 0, v[194:195]
	ds_read_b128 v[158:161], v237 offset:32768
	ds_read_b128 v[162:165], v237 offset:33792
	ds_read_b128 v[166:169], v237 offset:34816
	ds_read_b128 v[178:181], v237 offset:35840
	ds_read_b128 v[182:185], v237 offset:36864
	ds_read_b128 v[186:189], v237 offset:37888
	ds_read_b128 v[190:193], v237 offset:38912
	ds_read_b128 v[214:217], v237 offset:39936
	global_load_lds_dwordx4 v[226:227], off
	v_lshl_add_u64 v[226:227], s[0:1], 0, v[204:205]
	s_mov_b32 m0, s43
	s_nop 0
	global_load_lds_dwordx4 v[226:227], off
	s_waitcnt vmcnt(8)
	s_waitcnt lgkmcnt(0)
	s_barrier
	s_setprio 1
	s_waitcnt lgkmcnt(0)
	v_mfma_f32_16x16x32_bf16 v[174:177], v[78:81], v[158:161], v[174:177]
	v_mfma_f32_16x16x32_bf16 v[174:177], v[90:93], v[162:165], v[174:177]
	v_mfma_f32_16x16x32_bf16 v[138:141], v[90:93], v[178:181], v[138:141]
	v_mfma_f32_16x16x32_bf16 v[138:141], v[78:81], v[166:169], v[138:141]
	v_mfma_f32_16x16x32_bf16 v[110:113], v[78:81], v[182:185], v[110:113]
	v_mfma_f32_16x16x32_bf16 v[110:113], v[90:93], v[186:189], v[110:113]
	v_mfma_f32_16x16x32_bf16 v[86:89], v[90:93], v[214:217], v[86:89]
	v_mfma_f32_16x16x32_bf16 v[86:89], v[78:81], v[190:193], v[86:89]
	v_mfma_f32_16x16x32_bf16 v[82:85], v[102:105], v[190:193], v[82:85]
	v_mfma_f32_16x16x32_bf16 v[82:85], v[114:117], v[214:217], v[82:85]
	v_mfma_f32_16x16x32_bf16 v[106:109], v[114:117], v[186:189], v[106:109]
	v_mfma_f32_16x16x32_bf16 v[106:109], v[102:105], v[182:185], v[106:109]
	v_mfma_f32_16x16x32_bf16 v[130:133], v[102:105], v[166:169], v[130:133]
	v_mfma_f32_16x16x32_bf16 v[130:133], v[114:117], v[178:181], v[130:133]
	v_mfma_f32_16x16x32_bf16 v[170:173], v[114:117], v[162:165], v[170:173]
	v_mfma_f32_16x16x32_bf16 v[170:173], v[102:105], v[158:161], v[170:173]
	v_mfma_f32_16x16x32_bf16 v[150:153], v[126:129], v[158:161], v[150:153]
	v_mfma_f32_16x16x32_bf16 v[150:153], v[134:137], v[162:165], v[150:153]
	v_mfma_f32_16x16x32_bf16 v[122:125], v[134:137], v[178:181], v[122:125]
	v_mfma_f32_16x16x32_bf16 v[122:125], v[126:129], v[166:169], v[122:125]
	v_mfma_f32_16x16x32_bf16 v[98:101], v[126:129], v[182:185], v[98:101]
	v_mfma_f32_16x16x32_bf16 v[98:101], v[134:137], v[186:189], v[98:101]
	v_mfma_f32_16x16x32_bf16 v[74:77], v[134:137], v[214:217], v[74:77]
	v_mfma_f32_16x16x32_bf16 v[74:77], v[126:129], v[190:193], v[74:77]
	v_mfma_f32_16x16x32_bf16 v[66:69], v[142:145], v[190:193], v[66:69]
	v_mfma_f32_16x16x32_bf16 v[66:69], v[154:157], v[214:217], v[66:69]
	v_mfma_f32_16x16x32_bf16 v[94:97], v[154:157], v[186:189], v[94:97]
	v_mfma_f32_16x16x32_bf16 v[94:97], v[142:145], v[182:185], v[94:97]
	v_mfma_f32_16x16x32_bf16 v[118:121], v[142:145], v[166:169], v[118:121]
	v_mfma_f32_16x16x32_bf16 v[118:121], v[154:157], v[178:181], v[118:121]
	v_mfma_f32_16x16x32_bf16 v[146:149], v[154:157], v[162:165], v[146:149]
	v_mfma_f32_16x16x32_bf16 v[146:149], v[142:145], v[158:161], v[146:149]
	s_setprio 0
	s_barrier
	s_add_i32 s0, s18, s28
	v_lshl_add_u64 v[218:219], v[218:219], 0, s[82:83]
	s_mov_b32 m0, s0
	ds_read_b128 v[158:161], v237 offset:49152
	ds_read_b128 v[162:165], v237 offset:50176
	ds_read_b128 v[166:169], v237 offset:51200
	ds_read_b128 v[178:181], v237 offset:52224
	ds_read_b128 v[182:185], v237 offset:53248
	ds_read_b128 v[186:189], v237 offset:54272
	ds_read_b128 v[190:193], v237 offset:55296
	ds_read_b128 v[214:217], v237 offset:56320
	global_load_lds_dwordx4 v[218:219], off
	s_add_i32 m0, s0, 0x2000
	s_add_u32 s0, s70, 0x80080
	v_lshl_add_u64 v[218:219], v[220:221], 0, s[82:83]
	s_addc_u32 s1, s71, 0
	s_add_i32 s18, s19, s28
	global_load_lds_dwordx4 v[218:219], off
	v_lshl_add_u64 v[218:219], s[0:1], 0, v[194:195]
	s_mov_b32 m0, s18
	s_nop 0
	global_load_lds_dwordx4 v[218:219], off
	v_lshl_add_u64 v[218:219], s[0:1], 0, v[204:205]
	s_add_i32 m0, s18, 0x2000
	s_nop 0
	global_load_lds_dwordx4 v[218:219], off
	v_lshl_add_u64 v[218:219], v[222:223], 0, s[82:83]
	s_mov_b32 m0, s68
	s_nop 0
	global_load_lds_dwordx4 v[218:219], off
	v_lshl_add_u64 v[218:219], v[224:225], 0, s[82:83]
	s_mov_b32 m0, s79
	s_nop 0
	global_load_lds_dwordx4 v[218:219], off
	s_waitcnt vmcnt(8)
	s_waitcnt lgkmcnt(0)
	s_barrier
	s_setprio 1
	s_waitcnt lgkmcnt(0)
	v_mfma_f32_16x16x32_bf16 v[62:65], v[78:81], v[158:161], v[62:65]
	v_mfma_f32_16x16x32_bf16 v[62:65], v[90:93], v[162:165], v[62:65]
	v_mfma_f32_16x16x32_bf16 v[46:49], v[90:93], v[178:181], v[46:49]
	v_mfma_f32_16x16x32_bf16 v[46:49], v[78:81], v[166:169], v[46:49]
	v_mfma_f32_16x16x32_bf16 v[30:33], v[78:81], v[182:185], v[30:33]
	v_mfma_f32_16x16x32_bf16 v[30:33], v[90:93], v[186:189], v[30:33]
	v_mfma_f32_16x16x32_bf16 v[14:17], v[90:93], v[214:217], v[14:17]
	v_mfma_f32_16x16x32_bf16 v[14:17], v[78:81], v[190:193], v[14:17]
	v_mfma_f32_16x16x32_bf16 v[10:13], v[102:105], v[190:193], v[10:13]
	v_mfma_f32_16x16x32_bf16 v[10:13], v[114:117], v[214:217], v[10:13]
	v_mfma_f32_16x16x32_bf16 v[26:29], v[114:117], v[186:189], v[26:29]
	v_mfma_f32_16x16x32_bf16 v[26:29], v[102:105], v[182:185], v[26:29]
	v_mfma_f32_16x16x32_bf16 v[42:45], v[102:105], v[166:169], v[42:45]
	v_mfma_f32_16x16x32_bf16 v[42:45], v[114:117], v[178:181], v[42:45]
	v_mfma_f32_16x16x32_bf16 v[58:61], v[114:117], v[162:165], v[58:61]
	v_mfma_f32_16x16x32_bf16 v[58:61], v[102:105], v[158:161], v[58:61]
	v_mfma_f32_16x16x32_bf16 v[54:57], v[126:129], v[158:161], v[54:57]
	v_mfma_f32_16x16x32_bf16 v[54:57], v[134:137], v[162:165], v[54:57]
	v_mfma_f32_16x16x32_bf16 v[38:41], v[134:137], v[178:181], v[38:41]
	v_mfma_f32_16x16x32_bf16 v[38:41], v[126:129], v[166:169], v[38:41]
	v_mfma_f32_16x16x32_bf16 v[22:25], v[126:129], v[182:185], v[22:25]
	v_mfma_f32_16x16x32_bf16 v[22:25], v[134:137], v[186:189], v[22:25]
	v_mfma_f32_16x16x32_bf16 v[6:9], v[134:137], v[214:217], v[6:9]
	v_mfma_f32_16x16x32_bf16 v[6:9], v[126:129], v[190:193], v[6:9]
	v_mfma_f32_16x16x32_bf16 v[2:5], v[142:145], v[190:193], v[2:5]
	v_mfma_f32_16x16x32_bf16 v[2:5], v[154:157], v[214:217], v[2:5]
	v_mfma_f32_16x16x32_bf16 v[18:21], v[154:157], v[186:189], v[18:21]
	v_mfma_f32_16x16x32_bf16 v[18:21], v[142:145], v[182:185], v[18:21]
	v_mfma_f32_16x16x32_bf16 v[34:37], v[142:145], v[166:169], v[34:37]
	v_mfma_f32_16x16x32_bf16 v[34:37], v[154:157], v[178:181], v[34:37]
	v_mfma_f32_16x16x32_bf16 v[50:53], v[154:157], v[162:165], v[50:53]
	v_mfma_f32_16x16x32_bf16 v[50:53], v[142:145], v[158:161], v[50:53]
	s_setprio 0
	s_barrier
	s_add_i32 s57, s57, 2
	s_add_u32 s51, s51, 0x100
	s_addc_u32 s53, s53, 0
	s_cmp_gt_u32 s57, 29
	s_mov_b64 s[76:77], s[90:91]
	s_cbranch_scc1 .LBB0_512

.LBB0_581:
	s_add_u32 s18, s62, 0xfff80080
	s_addc_u32 s19, s63, -1
	s_and_b64 s[0:1], s[64:65], exec
	s_cselect_b32 s71, s22, s19
	s_cselect_b32 s70, s23, s18
	s_cselect_b32 s65, s39, s58
	s_cselect_b32 s64, s47, s53
	s_add_i32 s0, 0, 0x10000
	v_add_u32_e32 v153, s0, v1
	s_add_i32 s18, 0, 0x14000
	ds_read_b128 v[144:147], v153
	ds_read_b128 v[148:151], v153 offset:1024
	ds_read_b128 v[154:157], v153 offset:2048
	ds_read_b128 v[158:161], v153 offset:3072
	v_add_u32_e32 v153, s18, v1
	ds_read_b128 v[162:165], v153
	ds_read_b128 v[166:169], v153 offset:1024
	ds_read_b128 v[170:173], v153 offset:2048
	ds_read_b128 v[174:177], v153 offset:3072
	v_lshl_add_u64 v[220:221], s[62:63], 0, v[136:137]
	s_add_i32 m0, s29, 0xc000
	ds_read_b128 v[178:181], v152
	ds_read_b128 v[182:185], v152 offset:1024
	ds_read_b128 v[186:189], v152 offset:2048
	ds_read_b128 v[190:193], v152 offset:3072
	ds_read_b128 v[204:207], v152 offset:4096
	ds_read_b128 v[208:211], v152 offset:5120
	ds_read_b128 v[212:215], v152 offset:6144
	ds_read_b128 v[216:219], v152 offset:7168
	global_load_lds_dwordx4 v[220:221], off
	v_lshl_add_u64 v[220:221], s[62:63], 0, v[138:139]
	s_add_i32 m0, s29, 0xe000
	s_nop 0
	global_load_lds_dwordx4 v[220:221], off
	s_waitcnt vmcnt(8)
	s_waitcnt lgkmcnt(0)
	s_barrier
	s_setprio 1
	s_waitcnt lgkmcnt(0)
	v_mfma_f32_16x16x32_bf16 v[126:129], v[144:147], v[178:181], v[126:129]
	v_mfma_f32_16x16x32_bf16 v[126:129], v[148:151], v[182:185], v[126:129]
	v_mfma_f32_16x16x32_bf16 v[110:113], v[148:151], v[190:193], v[110:113]
	v_mfma_f32_16x16x32_bf16 v[110:113], v[144:147], v[186:189], v[110:113]
	v_mfma_f32_16x16x32_bf16 v[94:97], v[144:147], v[204:207], v[94:97]
	v_mfma_f32_16x16x32_bf16 v[94:97], v[148:151], v[208:211], v[94:97]
	v_mfma_f32_16x16x32_bf16 v[78:81], v[148:151], v[216:219], v[78:81]
	v_mfma_f32_16x16x32_bf16 v[78:81], v[144:147], v[212:215], v[78:81]
	v_mfma_f32_16x16x32_bf16 v[74:77], v[154:157], v[212:215], v[74:77]
	v_mfma_f32_16x16x32_bf16 v[74:77], v[158:161], v[216:219], v[74:77]
	v_mfma_f32_16x16x32_bf16 v[90:93], v[158:161], v[208:211], v[90:93]
	v_mfma_f32_16x16x32_bf16 v[90:93], v[154:157], v[204:207], v[90:93]
	v_mfma_f32_16x16x32_bf16 v[106:109], v[154:157], v[186:189], v[106:109]
	v_mfma_f32_16x16x32_bf16 v[106:109], v[158:161], v[190:193], v[106:109]
	v_mfma_f32_16x16x32_bf16 v[122:125], v[158:161], v[182:185], v[122:125]
	v_mfma_f32_16x16x32_bf16 v[122:125], v[154:157], v[178:181], v[122:125]
	v_mfma_f32_16x16x32_bf16 v[118:121], v[162:165], v[178:181], v[118:121]
	v_mfma_f32_16x16x32_bf16 v[118:121], v[166:169], v[182:185], v[118:121]
	v_mfma_f32_16x16x32_bf16 v[102:105], v[166:169], v[190:193], v[102:105]
	v_mfma_f32_16x16x32_bf16 v[102:105], v[162:165], v[186:189], v[102:105]
	v_mfma_f32_16x16x32_bf16 v[86:89], v[162:165], v[204:207], v[86:89]
	v_mfma_f32_16x16x32_bf16 v[86:89], v[166:169], v[208:211], v[86:89]
	v_mfma_f32_16x16x32_bf16 v[70:73], v[166:169], v[216:219], v[70:73]
	v_mfma_f32_16x16x32_bf16 v[70:73], v[162:165], v[212:215], v[70:73]
	v_mfma_f32_16x16x32_bf16 v[66:69], v[170:173], v[212:215], v[66:69]
	v_mfma_f32_16x16x32_bf16 v[66:69], v[174:177], v[216:219], v[66:69]
	v_mfma_f32_16x16x32_bf16 v[82:85], v[174:177], v[208:211], v[82:85]
	v_mfma_f32_16x16x32_bf16 v[82:85], v[170:173], v[204:207], v[82:85]
	v_mfma_f32_16x16x32_bf16 v[98:101], v[170:173], v[186:189], v[98:101]
	v_mfma_f32_16x16x32_bf16 v[98:101], v[174:177], v[190:193], v[98:101]
	v_mfma_f32_16x16x32_bf16 v[114:117], v[174:177], v[182:185], v[114:117]
	v_mfma_f32_16x16x32_bf16 v[114:117], v[170:173], v[178:181], v[114:117]
	s_setprio 0
	s_barrier
	s_add_i32 s0, s0, s28
	v_lshl_add_u64 v[220:221], s[64:65], 0, v[194:195]
	s_mov_b32 m0, s0
	ds_read_b128 v[178:181], v152 offset:16384
	ds_read_b128 v[182:185], v152 offset:17408
	ds_read_b128 v[186:189], v152 offset:18432
	ds_read_b128 v[190:193], v152 offset:19456
	ds_read_b128 v[204:207], v152 offset:20480
	ds_read_b128 v[208:211], v152 offset:21504
	ds_read_b128 v[212:215], v152 offset:22528
	ds_read_b128 v[216:219], v152 offset:23552
	global_load_lds_dwordx4 v[220:221], off
	s_add_i32 m0, s0, 0x2000
	s_add_u32 s0, s64, 0x80000
	v_lshl_add_u64 v[222:223], s[64:65], 0, v[130:131]
	s_addc_u32 s1, s65, 0
	s_add_i32 s18, s18, s28
	global_load_lds_dwordx4 v[222:223], off
	v_lshl_add_u64 v[224:225], s[0:1], 0, v[194:195]
	s_mov_b32 m0, s18
	v_lshl_add_u64 v[226:227], s[70:71], 0, v[130:131]
	global_load_lds_dwordx4 v[224:225], off
	v_lshl_add_u64 v[224:225], s[0:1], 0, v[130:131]
	s_add_i32 m0, s18, 0x2000
	s_nop 0
	global_load_lds_dwordx4 v[224:225], off
	v_lshl_add_u64 v[224:225], s[70:71], 0, v[194:195]
	s_mov_b32 m0, s29
	s_nop 0
	global_load_lds_dwordx4 v[224:225], off
	s_mov_b32 m0, s31
	s_nop 0
	global_load_lds_dwordx4 v[226:227], off
	s_waitcnt vmcnt(8)
	s_waitcnt lgkmcnt(0)
	s_barrier
	s_setprio 1
	s_waitcnt lgkmcnt(0)
	v_mfma_f32_16x16x32_bf16 v[62:65], v[144:147], v[178:181], v[62:65]
	v_mfma_f32_16x16x32_bf16 v[62:65], v[148:151], v[182:185], v[62:65]
	v_mfma_f32_16x16x32_bf16 v[46:49], v[148:151], v[190:193], v[46:49]
	v_mfma_f32_16x16x32_bf16 v[46:49], v[144:147], v[186:189], v[46:49]
	v_mfma_f32_16x16x32_bf16 v[30:33], v[144:147], v[204:207], v[30:33]
	v_mfma_f32_16x16x32_bf16 v[30:33], v[148:151], v[208:211], v[30:33]
	v_mfma_f32_16x16x32_bf16 v[14:17], v[148:151], v[216:219], v[14:17]
	v_mfma_f32_16x16x32_bf16 v[14:17], v[144:147], v[212:215], v[14:17]
	v_mfma_f32_16x16x32_bf16 v[10:13], v[154:157], v[212:215], v[10:13]
	v_mfma_f32_16x16x32_bf16 v[10:13], v[158:161], v[216:219], v[10:13]
	v_mfma_f32_16x16x32_bf16 v[26:29], v[158:161], v[208:211], v[26:29]
	v_mfma_f32_16x16x32_bf16 v[26:29], v[154:157], v[204:207], v[26:29]
	v_mfma_f32_16x16x32_bf16 v[42:45], v[154:157], v[186:189], v[42:45]
	v_mfma_f32_16x16x32_bf16 v[42:45], v[158:161], v[190:193], v[42:45]
	v_mfma_f32_16x16x32_bf16 v[58:61], v[158:161], v[182:185], v[58:61]
	v_mfma_f32_16x16x32_bf16 v[58:61], v[154:157], v[178:181], v[58:61]
	v_mfma_f32_16x16x32_bf16 v[54:57], v[162:165], v[178:181], v[54:57]
	v_mfma_f32_16x16x32_bf16 v[54:57], v[166:169], v[182:185], v[54:57]
	v_mfma_f32_16x16x32_bf16 v[38:41], v[166:169], v[190:193], v[38:41]
	v_mfma_f32_16x16x32_bf16 v[38:41], v[162:165], v[186:189], v[38:41]
	v_mfma_f32_16x16x32_bf16 v[22:25], v[162:165], v[204:207], v[22:25]
	v_mfma_f32_16x16x32_bf16 v[22:25], v[166:169], v[208:211], v[22:25]
	v_mfma_f32_16x16x32_bf16 v[6:9], v[166:169], v[216:219], v[6:9]
	v_mfma_f32_16x16x32_bf16 v[6:9], v[162:165], v[212:215], v[6:9]
	v_mfma_f32_16x16x32_bf16 v[2:5], v[170:173], v[212:215], v[2:5]
	v_mfma_f32_16x16x32_bf16 v[2:5], v[174:177], v[216:219], v[2:5]
	v_mfma_f32_16x16x32_bf16 v[18:21], v[174:177], v[208:211], v[18:21]
	v_mfma_f32_16x16x32_bf16 v[18:21], v[170:173], v[204:207], v[18:21]
	v_mfma_f32_16x16x32_bf16 v[34:37], v[170:173], v[186:189], v[34:37]
	v_mfma_f32_16x16x32_bf16 v[34:37], v[174:177], v[190:193], v[34:37]
	v_mfma_f32_16x16x32_bf16 v[50:53], v[174:177], v[182:185], v[50:53]
	v_mfma_f32_16x16x32_bf16 v[50:53], v[170:173], v[178:181], v[50:53]
	s_setprio 0
	s_barrier
	s_add_i32 s18, 0, 0x18000
	v_add_u32_e32 v153, s18, v1
	s_add_i32 s19, 0, 0x1c000
	ds_read_b128 v[144:147], v153
	ds_read_b128 v[148:151], v153 offset:1024
	ds_read_b128 v[154:157], v153 offset:2048
	ds_read_b128 v[158:161], v153 offset:3072
	v_add_u32_e32 v153, s19, v1
	ds_read_b128 v[162:165], v153
	ds_read_b128 v[166:169], v153 offset:1024
	ds_read_b128 v[170:173], v153 offset:2048
	ds_read_b128 v[174:177], v153 offset:3072
	s_add_u32 s0, s70, 0x80000
	s_addc_u32 s1, s71, 0
	s_mov_b32 m0, s33
	v_lshl_add_u64 v[228:229], s[0:1], 0, v[194:195]
	ds_read_b128 v[178:181], v152 offset:32768
	ds_read_b128 v[182:185], v152 offset:33792
	ds_read_b128 v[186:189], v152 offset:34816
	ds_read_b128 v[190:193], v152 offset:35840
	ds_read_b128 v[204:207], v152 offset:36864
	ds_read_b128 v[208:211], v152 offset:37888
	ds_read_b128 v[212:215], v152 offset:38912
	ds_read_b128 v[216:219], v152 offset:39936
	global_load_lds_dwordx4 v[228:229], off
	v_lshl_add_u64 v[228:229], s[0:1], 0, v[130:131]
	s_mov_b32 m0, s40
	s_nop 0
	global_load_lds_dwordx4 v[228:229], off
	s_waitcnt vmcnt(8)
	s_waitcnt lgkmcnt(0)
	s_barrier
	s_setprio 1
	s_waitcnt lgkmcnt(0)
	v_mfma_f32_16x16x32_bf16 v[126:129], v[144:147], v[178:181], v[126:129]
	v_mfma_f32_16x16x32_bf16 v[126:129], v[148:151], v[182:185], v[126:129]
	v_mfma_f32_16x16x32_bf16 v[110:113], v[148:151], v[190:193], v[110:113]
	v_mfma_f32_16x16x32_bf16 v[110:113], v[144:147], v[186:189], v[110:113]
	v_mfma_f32_16x16x32_bf16 v[94:97], v[144:147], v[204:207], v[94:97]
	v_mfma_f32_16x16x32_bf16 v[94:97], v[148:151], v[208:211], v[94:97]
	v_mfma_f32_16x16x32_bf16 v[78:81], v[148:151], v[216:219], v[78:81]
	v_mfma_f32_16x16x32_bf16 v[78:81], v[144:147], v[212:215], v[78:81]
	v_mfma_f32_16x16x32_bf16 v[74:77], v[154:157], v[212:215], v[74:77]
	v_mfma_f32_16x16x32_bf16 v[74:77], v[158:161], v[216:219], v[74:77]
	v_mfma_f32_16x16x32_bf16 v[90:93], v[158:161], v[208:211], v[90:93]
	v_mfma_f32_16x16x32_bf16 v[90:93], v[154:157], v[204:207], v[90:93]
	v_mfma_f32_16x16x32_bf16 v[106:109], v[154:157], v[186:189], v[106:109]
	v_mfma_f32_16x16x32_bf16 v[106:109], v[158:161], v[190:193], v[106:109]
	v_mfma_f32_16x16x32_bf16 v[122:125], v[158:161], v[182:185], v[122:125]
	v_mfma_f32_16x16x32_bf16 v[122:125], v[154:157], v[178:181], v[122:125]
	v_mfma_f32_16x16x32_bf16 v[118:121], v[162:165], v[178:181], v[118:121]
	v_mfma_f32_16x16x32_bf16 v[118:121], v[166:169], v[182:185], v[118:121]
	v_mfma_f32_16x16x32_bf16 v[102:105], v[166:169], v[190:193], v[102:105]
	v_mfma_f32_16x16x32_bf16 v[102:105], v[162:165], v[186:189], v[102:105]
	v_mfma_f32_16x16x32_bf16 v[86:89], v[162:165], v[204:207], v[86:89]
	v_mfma_f32_16x16x32_bf16 v[86:89], v[166:169], v[208:211], v[86:89]
	v_mfma_f32_16x16x32_bf16 v[70:73], v[166:169], v[216:219], v[70:73]
	v_mfma_f32_16x16x32_bf16 v[70:73], v[162:165], v[212:215], v[70:73]
	v_mfma_f32_16x16x32_bf16 v[66:69], v[170:173], v[212:215], v[66:69]
	v_mfma_f32_16x16x32_bf16 v[66:69], v[174:177], v[216:219], v[66:69]
	v_mfma_f32_16x16x32_bf16 v[82:85], v[174:177], v[208:211], v[82:85]
	v_mfma_f32_16x16x32_bf16 v[82:85], v[170:173], v[204:207], v[82:85]
	v_mfma_f32_16x16x32_bf16 v[98:101], v[170:173], v[186:189], v[98:101]
	v_mfma_f32_16x16x32_bf16 v[98:101], v[174:177], v[190:193], v[98:101]
	v_mfma_f32_16x16x32_bf16 v[114:117], v[174:177], v[182:185], v[114:117]
	v_mfma_f32_16x16x32_bf16 v[114:117], v[170:173], v[178:181], v[114:117]
	s_setprio 0
	s_barrier
	s_add_i32 s0, s18, s28
	v_lshl_add_u64 v[220:221], v[220:221], 0, s[82:83]
	s_mov_b32 m0, s0
	ds_read_b128 v[178:181], v152 offset:49152
	ds_read_b128 v[182:185], v152 offset:50176
	ds_read_b128 v[186:189], v152 offset:51200
	ds_read_b128 v[190:193], v152 offset:52224
	ds_read_b128 v[204:207], v152 offset:53248
	ds_read_b128 v[208:211], v152 offset:54272
	ds_read_b128 v[212:215], v152 offset:55296
	ds_read_b128 v[216:219], v152 offset:56320
	global_load_lds_dwordx4 v[220:221], off
	s_add_i32 m0, s0, 0x2000
	s_add_u32 s0, s64, 0x80080
	v_lshl_add_u64 v[220:221], v[222:223], 0, s[82:83]
	s_addc_u32 s1, s65, 0
	s_add_i32 s18, s19, s28
	global_load_lds_dwordx4 v[220:221], off
	v_lshl_add_u64 v[220:221], s[0:1], 0, v[194:195]
	s_mov_b32 m0, s18
	s_nop 0
	global_load_lds_dwordx4 v[220:221], off
	v_lshl_add_u64 v[220:221], s[0:1], 0, v[130:131]
	s_add_i32 m0, s18, 0x2000
	s_nop 0
	global_load_lds_dwordx4 v[220:221], off
	v_lshl_add_u64 v[220:221], v[224:225], 0, s[82:83]
	s_mov_b32 m0, s54
	s_nop 0
	global_load_lds_dwordx4 v[220:221], off
	v_lshl_add_u64 v[220:221], v[226:227], 0, s[82:83]
	s_mov_b32 m0, s57
	s_nop 0
	global_load_lds_dwordx4 v[220:221], off
	s_waitcnt vmcnt(8)
	s_waitcnt lgkmcnt(0)
	s_barrier
	s_setprio 1
	s_waitcnt lgkmcnt(0)
	v_mfma_f32_16x16x32_bf16 v[62:65], v[144:147], v[178:181], v[62:65]
	v_mfma_f32_16x16x32_bf16 v[62:65], v[148:151], v[182:185], v[62:65]
	v_mfma_f32_16x16x32_bf16 v[46:49], v[148:151], v[190:193], v[46:49]
	v_mfma_f32_16x16x32_bf16 v[46:49], v[144:147], v[186:189], v[46:49]
	v_mfma_f32_16x16x32_bf16 v[30:33], v[144:147], v[204:207], v[30:33]
	v_mfma_f32_16x16x32_bf16 v[30:33], v[148:151], v[208:211], v[30:33]
	v_mfma_f32_16x16x32_bf16 v[14:17], v[148:151], v[216:219], v[14:17]
	v_mfma_f32_16x16x32_bf16 v[14:17], v[144:147], v[212:215], v[14:17]
	v_mfma_f32_16x16x32_bf16 v[10:13], v[154:157], v[212:215], v[10:13]
	v_mfma_f32_16x16x32_bf16 v[10:13], v[158:161], v[216:219], v[10:13]
	v_mfma_f32_16x16x32_bf16 v[26:29], v[158:161], v[208:211], v[26:29]
	v_mfma_f32_16x16x32_bf16 v[26:29], v[154:157], v[204:207], v[26:29]
	v_mfma_f32_16x16x32_bf16 v[42:45], v[154:157], v[186:189], v[42:45]
	v_mfma_f32_16x16x32_bf16 v[42:45], v[158:161], v[190:193], v[42:45]
	v_mfma_f32_16x16x32_bf16 v[58:61], v[158:161], v[182:185], v[58:61]
	v_mfma_f32_16x16x32_bf16 v[58:61], v[154:157], v[178:181], v[58:61]
	v_mfma_f32_16x16x32_bf16 v[54:57], v[162:165], v[178:181], v[54:57]
	v_mfma_f32_16x16x32_bf16 v[54:57], v[166:169], v[182:185], v[54:57]
	v_mfma_f32_16x16x32_bf16 v[38:41], v[166:169], v[190:193], v[38:41]
	v_mfma_f32_16x16x32_bf16 v[38:41], v[162:165], v[186:189], v[38:41]
	v_mfma_f32_16x16x32_bf16 v[22:25], v[162:165], v[204:207], v[22:25]
	v_mfma_f32_16x16x32_bf16 v[22:25], v[166:169], v[208:211], v[22:25]
	v_mfma_f32_16x16x32_bf16 v[6:9], v[166:169], v[216:219], v[6:9]
	v_mfma_f32_16x16x32_bf16 v[6:9], v[162:165], v[212:215], v[6:9]
	v_mfma_f32_16x16x32_bf16 v[2:5], v[170:173], v[212:215], v[2:5]
	v_mfma_f32_16x16x32_bf16 v[2:5], v[174:177], v[216:219], v[2:5]
	v_mfma_f32_16x16x32_bf16 v[18:21], v[174:177], v[208:211], v[18:21]
	v_mfma_f32_16x16x32_bf16 v[18:21], v[170:173], v[204:207], v[18:21]
	v_mfma_f32_16x16x32_bf16 v[34:37], v[170:173], v[186:189], v[34:37]
	v_mfma_f32_16x16x32_bf16 v[34:37], v[174:177], v[190:193], v[34:37]
	v_mfma_f32_16x16x32_bf16 v[50:53], v[174:177], v[182:185], v[50:53]
	v_mfma_f32_16x16x32_bf16 v[50:53], v[170:173], v[178:181], v[50:53]
	s_setprio 0
	s_barrier
	s_add_i32 s76, s76, 2
	s_add_u32 s62, s62, 0x100
	s_addc_u32 s63, s63, 0
	s_add_u32 s53, s53, 0x100
	s_addc_u32 s58, s58, 0
	s_cmp_gt_u32 s76, 29
	s_cbranch_scc1 .LBB0_584

.LBB0_645:
	s_add_u32 s64, s8, 0x100
	s_addc_u32 s65, s9, 0
	s_and_b64 s[0:1], s[70:71], exec
	s_cselect_b32 s77, s63, s65
	s_cselect_b32 s76, s62, s64
	s_cselect_b32 s71, s85, s23
	s_cselect_b32 s70, s84, s7
	s_add_i32 s0, 0, 0x10000
	s_add_i32 s18, 0, 0x14000
	v_add_u32_e32 v106, s0, v1
	v_add_u32_e32 v154, s18, v1
	ds_read_b128 v[70:73], v106
	ds_read_b128 v[82:85], v106 offset:1024
	ds_read_b128 v[94:97], v106 offset:2048
	ds_read_b128 v[106:109], v106 offset:3072
	ds_read_b128 v[118:121], v154
	ds_read_b128 v[130:133], v154 offset:1024
	ds_read_b128 v[142:145], v154 offset:2048
	ds_read_b128 v[154:157], v154 offset:3072
	v_lshl_add_u64 v[218:219], s[8:9], 0, v[206:207]
	s_add_i32 m0, s29, 0xc000
	ds_read_b128 v[158:161], v237
	ds_read_b128 v[170:173], v237 offset:1024
	ds_read_b128 v[174:177], v237 offset:2048
	ds_read_b128 v[178:181], v237 offset:3072
	ds_read_b128 v[182:185], v237 offset:4096
	ds_read_b128 v[186:189], v237 offset:5120
	ds_read_b128 v[210:213], v237 offset:6144
	ds_read_b128 v[214:217], v237 offset:7168
	global_load_lds_dwordx4 v[218:219], off
	v_lshl_add_u64 v[218:219], s[8:9], 0, v[208:209]
	s_add_i32 m0, s29, 0xe000
	s_nop 0
	global_load_lds_dwordx4 v[218:219], off
	s_waitcnt vmcnt(8)
	s_waitcnt lgkmcnt(0)
	s_barrier
	s_setprio 1
	s_waitcnt lgkmcnt(0)
	v_mfma_f32_16x16x32_bf16 v[166:169], v[70:73], v[158:161], v[166:169]
	v_mfma_f32_16x16x32_bf16 v[166:169], v[82:85], v[170:173], v[166:169]
	v_mfma_f32_16x16x32_bf16 v[138:141], v[82:85], v[178:181], v[138:141]
	v_mfma_f32_16x16x32_bf16 v[138:141], v[70:73], v[174:177], v[138:141]
	v_mfma_f32_16x16x32_bf16 v[114:117], v[70:73], v[182:185], v[114:117]
	v_mfma_f32_16x16x32_bf16 v[114:117], v[82:85], v[186:189], v[114:117]
	v_mfma_f32_16x16x32_bf16 v[90:93], v[82:85], v[214:217], v[90:93]
	v_mfma_f32_16x16x32_bf16 v[90:93], v[70:73], v[210:213], v[90:93]
	v_mfma_f32_16x16x32_bf16 v[86:89], v[94:97], v[210:213], v[86:89]
	v_mfma_f32_16x16x32_bf16 v[86:89], v[106:109], v[214:217], v[86:89]
	v_mfma_f32_16x16x32_bf16 v[110:113], v[106:109], v[186:189], v[110:113]
	v_mfma_f32_16x16x32_bf16 v[110:113], v[94:97], v[182:185], v[110:113]
	v_mfma_f32_16x16x32_bf16 v[134:137], v[94:97], v[174:177], v[134:137]
	v_mfma_f32_16x16x32_bf16 v[134:137], v[106:109], v[178:181], v[134:137]
	v_mfma_f32_16x16x32_bf16 v[162:165], v[106:109], v[170:173], v[162:165]
	v_mfma_f32_16x16x32_bf16 v[162:165], v[94:97], v[158:161], v[162:165]
	v_mfma_f32_16x16x32_bf16 v[150:153], v[118:121], v[158:161], v[150:153]
	v_mfma_f32_16x16x32_bf16 v[150:153], v[130:133], v[170:173], v[150:153]
	v_mfma_f32_16x16x32_bf16 v[126:129], v[130:133], v[178:181], v[126:129]
	v_mfma_f32_16x16x32_bf16 v[126:129], v[118:121], v[174:177], v[126:129]
	v_mfma_f32_16x16x32_bf16 v[102:105], v[118:121], v[182:185], v[102:105]
	v_mfma_f32_16x16x32_bf16 v[102:105], v[130:133], v[186:189], v[102:105]
	v_mfma_f32_16x16x32_bf16 v[78:81], v[130:133], v[214:217], v[78:81]
	v_mfma_f32_16x16x32_bf16 v[78:81], v[118:121], v[210:213], v[78:81]
	v_mfma_f32_16x16x32_bf16 v[74:77], v[142:145], v[210:213], v[74:77]
	v_mfma_f32_16x16x32_bf16 v[74:77], v[154:157], v[214:217], v[74:77]
	v_mfma_f32_16x16x32_bf16 v[98:101], v[154:157], v[186:189], v[98:101]
	v_mfma_f32_16x16x32_bf16 v[98:101], v[142:145], v[182:185], v[98:101]
	v_mfma_f32_16x16x32_bf16 v[122:125], v[142:145], v[174:177], v[122:125]
	v_mfma_f32_16x16x32_bf16 v[122:125], v[154:157], v[178:181], v[122:125]
	v_mfma_f32_16x16x32_bf16 v[146:149], v[154:157], v[170:173], v[146:149]
	v_mfma_f32_16x16x32_bf16 v[146:149], v[142:145], v[158:161], v[146:149]
	s_setprio 0
	s_barrier
	s_add_i32 s0, s0, s28
	v_lshl_add_u64 v[218:219], s[70:71], 0, v[192:193]
	s_mov_b32 m0, s0
	ds_read_b128 v[158:161], v237 offset:16384
	ds_read_b128 v[170:173], v237 offset:17408
	ds_read_b128 v[174:177], v237 offset:18432
	ds_read_b128 v[178:181], v237 offset:19456
	ds_read_b128 v[182:185], v237 offset:20480
	ds_read_b128 v[186:189], v237 offset:21504
	ds_read_b128 v[210:213], v237 offset:22528
	ds_read_b128 v[214:217], v237 offset:23552
	global_load_lds_dwordx4 v[218:219], off
	s_add_i32 m0, s0, 0x2000
	s_add_u32 s0, s70, 0x160000
	v_lshl_add_u64 v[220:221], s[70:71], 0, v[190:191]
	s_addc_u32 s1, s71, 0
	s_add_i32 s8, s18, s28
	global_load_lds_dwordx4 v[220:221], off
	v_lshl_add_u64 v[222:223], s[0:1], 0, v[192:193]
	s_mov_b32 m0, s8
	v_lshl_add_u64 v[224:225], s[76:77], 0, v[190:191]
	global_load_lds_dwordx4 v[222:223], off
	v_lshl_add_u64 v[222:223], s[0:1], 0, v[190:191]
	s_add_i32 m0, s8, 0x2000
	s_nop 0
	global_load_lds_dwordx4 v[222:223], off
	v_lshl_add_u64 v[222:223], s[76:77], 0, v[192:193]
	s_mov_b32 m0, s29
	s_nop 0
	global_load_lds_dwordx4 v[222:223], off
	s_mov_b32 m0, s31
	s_nop 0
	global_load_lds_dwordx4 v[224:225], off
	s_waitcnt vmcnt(8)
	s_waitcnt lgkmcnt(0)
	s_barrier
	s_setprio 1
	s_waitcnt lgkmcnt(0)
	v_mfma_f32_16x16x32_bf16 v[62:65], v[70:73], v[158:161], v[62:65]
	v_mfma_f32_16x16x32_bf16 v[62:65], v[82:85], v[170:173], v[62:65]
	v_mfma_f32_16x16x32_bf16 v[46:49], v[82:85], v[178:181], v[46:49]
	v_mfma_f32_16x16x32_bf16 v[46:49], v[70:73], v[174:177], v[46:49]
	v_mfma_f32_16x16x32_bf16 v[30:33], v[70:73], v[182:185], v[30:33]
	v_mfma_f32_16x16x32_bf16 v[30:33], v[82:85], v[186:189], v[30:33]
	v_mfma_f32_16x16x32_bf16 v[14:17], v[82:85], v[214:217], v[14:17]
	v_mfma_f32_16x16x32_bf16 v[14:17], v[70:73], v[210:213], v[14:17]
	v_mfma_f32_16x16x32_bf16 v[10:13], v[94:97], v[210:213], v[10:13]
	v_mfma_f32_16x16x32_bf16 v[10:13], v[106:109], v[214:217], v[10:13]
	v_mfma_f32_16x16x32_bf16 v[26:29], v[106:109], v[186:189], v[26:29]
	v_mfma_f32_16x16x32_bf16 v[26:29], v[94:97], v[182:185], v[26:29]
	v_mfma_f32_16x16x32_bf16 v[42:45], v[94:97], v[174:177], v[42:45]
	v_mfma_f32_16x16x32_bf16 v[42:45], v[106:109], v[178:181], v[42:45]
	v_mfma_f32_16x16x32_bf16 v[58:61], v[106:109], v[170:173], v[58:61]
	v_mfma_f32_16x16x32_bf16 v[58:61], v[94:97], v[158:161], v[58:61]
	v_mfma_f32_16x16x32_bf16 v[54:57], v[118:121], v[158:161], v[54:57]
	v_mfma_f32_16x16x32_bf16 v[54:57], v[130:133], v[170:173], v[54:57]
	v_mfma_f32_16x16x32_bf16 v[38:41], v[130:133], v[178:181], v[38:41]
	v_mfma_f32_16x16x32_bf16 v[38:41], v[118:121], v[174:177], v[38:41]
	v_mfma_f32_16x16x32_bf16 v[22:25], v[118:121], v[182:185], v[22:25]
	v_mfma_f32_16x16x32_bf16 v[22:25], v[130:133], v[186:189], v[22:25]
	v_mfma_f32_16x16x32_bf16 v[6:9], v[130:133], v[214:217], v[6:9]
	v_mfma_f32_16x16x32_bf16 v[6:9], v[118:121], v[210:213], v[6:9]
	v_mfma_f32_16x16x32_bf16 v[2:5], v[142:145], v[210:213], v[2:5]
	v_mfma_f32_16x16x32_bf16 v[2:5], v[154:157], v[214:217], v[2:5]
	v_mfma_f32_16x16x32_bf16 v[18:21], v[154:157], v[186:189], v[18:21]
	v_mfma_f32_16x16x32_bf16 v[18:21], v[142:145], v[182:185], v[18:21]
	v_mfma_f32_16x16x32_bf16 v[34:37], v[142:145], v[174:177], v[34:37]
	v_mfma_f32_16x16x32_bf16 v[34:37], v[154:157], v[178:181], v[34:37]
	v_mfma_f32_16x16x32_bf16 v[50:53], v[154:157], v[170:173], v[50:53]
	v_mfma_f32_16x16x32_bf16 v[50:53], v[142:145], v[158:161], v[50:53]
	s_setprio 0
	s_barrier
	s_add_i32 s8, 0, 0x18000
	s_add_i32 s9, 0, 0x1c000
	v_add_u32_e32 v106, s8, v1
	v_add_u32_e32 v154, s9, v1
	ds_read_b128 v[70:73], v106
	ds_read_b128 v[82:85], v106 offset:1024
	ds_read_b128 v[94:97], v106 offset:2048
	ds_read_b128 v[106:109], v106 offset:3072
	ds_read_b128 v[118:121], v154
	ds_read_b128 v[130:133], v154 offset:1024
	ds_read_b128 v[142:145], v154 offset:2048
	ds_read_b128 v[154:157], v154 offset:3072
	s_add_u32 s0, s76, 0x160000
	s_addc_u32 s1, s77, 0
	s_mov_b32 m0, s33
	v_lshl_add_u64 v[226:227], s[0:1], 0, v[192:193]
	ds_read_b128 v[158:161], v237 offset:32768
	ds_read_b128 v[170:173], v237 offset:33792
	ds_read_b128 v[174:177], v237 offset:34816
	ds_read_b128 v[178:181], v237 offset:35840
	ds_read_b128 v[182:185], v237 offset:36864
	ds_read_b128 v[186:189], v237 offset:37888
	ds_read_b128 v[210:213], v237 offset:38912
	ds_read_b128 v[214:217], v237 offset:39936
	global_load_lds_dwordx4 v[226:227], off
	v_lshl_add_u64 v[226:227], s[0:1], 0, v[190:191]
	s_mov_b32 m0, s43
	s_nop 0
	global_load_lds_dwordx4 v[226:227], off
	s_waitcnt vmcnt(8)
	s_waitcnt lgkmcnt(0)
	s_barrier
	s_setprio 1
	s_waitcnt lgkmcnt(0)
	v_mfma_f32_16x16x32_bf16 v[166:169], v[70:73], v[158:161], v[166:169]
	v_mfma_f32_16x16x32_bf16 v[166:169], v[82:85], v[170:173], v[166:169]
	v_mfma_f32_16x16x32_bf16 v[138:141], v[82:85], v[178:181], v[138:141]
	v_mfma_f32_16x16x32_bf16 v[138:141], v[70:73], v[174:177], v[138:141]
	v_mfma_f32_16x16x32_bf16 v[114:117], v[70:73], v[182:185], v[114:117]
	v_mfma_f32_16x16x32_bf16 v[114:117], v[82:85], v[186:189], v[114:117]
	v_mfma_f32_16x16x32_bf16 v[90:93], v[82:85], v[214:217], v[90:93]
	v_mfma_f32_16x16x32_bf16 v[90:93], v[70:73], v[210:213], v[90:93]
	v_mfma_f32_16x16x32_bf16 v[86:89], v[94:97], v[210:213], v[86:89]
	v_mfma_f32_16x16x32_bf16 v[86:89], v[106:109], v[214:217], v[86:89]
	v_mfma_f32_16x16x32_bf16 v[110:113], v[106:109], v[186:189], v[110:113]
	v_mfma_f32_16x16x32_bf16 v[110:113], v[94:97], v[182:185], v[110:113]
	v_mfma_f32_16x16x32_bf16 v[134:137], v[94:97], v[174:177], v[134:137]
	v_mfma_f32_16x16x32_bf16 v[134:137], v[106:109], v[178:181], v[134:137]
	v_mfma_f32_16x16x32_bf16 v[162:165], v[106:109], v[170:173], v[162:165]
	v_mfma_f32_16x16x32_bf16 v[162:165], v[94:97], v[158:161], v[162:165]
	v_mfma_f32_16x16x32_bf16 v[150:153], v[118:121], v[158:161], v[150:153]
	v_mfma_f32_16x16x32_bf16 v[150:153], v[130:133], v[170:173], v[150:153]
	v_mfma_f32_16x16x32_bf16 v[126:129], v[130:133], v[178:181], v[126:129]
	v_mfma_f32_16x16x32_bf16 v[126:129], v[118:121], v[174:177], v[126:129]
	v_mfma_f32_16x16x32_bf16 v[102:105], v[118:121], v[182:185], v[102:105]
	v_mfma_f32_16x16x32_bf16 v[102:105], v[130:133], v[186:189], v[102:105]
	v_mfma_f32_16x16x32_bf16 v[78:81], v[130:133], v[214:217], v[78:81]
	v_mfma_f32_16x16x32_bf16 v[78:81], v[118:121], v[210:213], v[78:81]
	v_mfma_f32_16x16x32_bf16 v[74:77], v[142:145], v[210:213], v[74:77]
	v_mfma_f32_16x16x32_bf16 v[74:77], v[154:157], v[214:217], v[74:77]
	v_mfma_f32_16x16x32_bf16 v[98:101], v[154:157], v[186:189], v[98:101]
	v_mfma_f32_16x16x32_bf16 v[98:101], v[142:145], v[182:185], v[98:101]
	v_mfma_f32_16x16x32_bf16 v[122:125], v[142:145], v[174:177], v[122:125]
	v_mfma_f32_16x16x32_bf16 v[122:125], v[154:157], v[178:181], v[122:125]
	v_mfma_f32_16x16x32_bf16 v[146:149], v[154:157], v[170:173], v[146:149]
	v_mfma_f32_16x16x32_bf16 v[146:149], v[142:145], v[158:161], v[146:149]
	s_setprio 0
	s_barrier
	s_add_i32 s0, s8, s28
	v_lshl_add_u64 v[218:219], v[218:219], 0, s[82:83]
	s_mov_b32 m0, s0
	ds_read_b128 v[158:161], v237 offset:49152
	ds_read_b128 v[170:173], v237 offset:50176
	ds_read_b128 v[174:177], v237 offset:51200
	ds_read_b128 v[178:181], v237 offset:52224
	ds_read_b128 v[182:185], v237 offset:53248
	ds_read_b128 v[186:189], v237 offset:54272
	ds_read_b128 v[210:213], v237 offset:55296
	ds_read_b128 v[214:217], v237 offset:56320
	global_load_lds_dwordx4 v[218:219], off
	s_add_i32 m0, s0, 0x2000
	s_add_u32 s0, s70, 0x160080
	v_lshl_add_u64 v[218:219], v[220:221], 0, s[82:83]
	s_addc_u32 s1, s71, 0
	s_add_i32 s8, s9, s28
	global_load_lds_dwordx4 v[218:219], off
	v_lshl_add_u64 v[218:219], s[0:1], 0, v[192:193]
	s_mov_b32 m0, s8
	s_nop 0
	global_load_lds_dwordx4 v[218:219], off
	v_lshl_add_u64 v[218:219], s[0:1], 0, v[190:191]
	s_add_i32 m0, s8, 0x2000
	s_nop 0
	global_load_lds_dwordx4 v[218:219], off
	v_lshl_add_u64 v[218:219], v[222:223], 0, s[82:83]
	s_mov_b32 m0, s68
	s_nop 0
	global_load_lds_dwordx4 v[218:219], off
	v_lshl_add_u64 v[218:219], v[224:225], 0, s[82:83]
	s_mov_b32 m0, s79
	s_nop 0
	global_load_lds_dwordx4 v[218:219], off
	s_waitcnt vmcnt(8)
	s_waitcnt lgkmcnt(0)
	s_barrier
	s_setprio 1
	s_waitcnt lgkmcnt(0)
	v_mfma_f32_16x16x32_bf16 v[62:65], v[70:73], v[158:161], v[62:65]
	v_mfma_f32_16x16x32_bf16 v[62:65], v[82:85], v[170:173], v[62:65]
	v_mfma_f32_16x16x32_bf16 v[46:49], v[82:85], v[178:181], v[46:49]
	v_mfma_f32_16x16x32_bf16 v[46:49], v[70:73], v[174:177], v[46:49]
	v_mfma_f32_16x16x32_bf16 v[30:33], v[70:73], v[182:185], v[30:33]
	v_mfma_f32_16x16x32_bf16 v[30:33], v[82:85], v[186:189], v[30:33]
	v_mfma_f32_16x16x32_bf16 v[14:17], v[82:85], v[214:217], v[14:17]
	v_mfma_f32_16x16x32_bf16 v[14:17], v[70:73], v[210:213], v[14:17]
	v_mfma_f32_16x16x32_bf16 v[10:13], v[94:97], v[210:213], v[10:13]
	v_mfma_f32_16x16x32_bf16 v[10:13], v[106:109], v[214:217], v[10:13]
	v_mfma_f32_16x16x32_bf16 v[26:29], v[106:109], v[186:189], v[26:29]
	v_mfma_f32_16x16x32_bf16 v[26:29], v[94:97], v[182:185], v[26:29]
	v_mfma_f32_16x16x32_bf16 v[42:45], v[94:97], v[174:177], v[42:45]
	v_mfma_f32_16x16x32_bf16 v[42:45], v[106:109], v[178:181], v[42:45]
	v_mfma_f32_16x16x32_bf16 v[58:61], v[106:109], v[170:173], v[58:61]
	v_mfma_f32_16x16x32_bf16 v[58:61], v[94:97], v[158:161], v[58:61]
	v_mfma_f32_16x16x32_bf16 v[54:57], v[118:121], v[158:161], v[54:57]
	v_mfma_f32_16x16x32_bf16 v[54:57], v[130:133], v[170:173], v[54:57]
	v_mfma_f32_16x16x32_bf16 v[38:41], v[130:133], v[178:181], v[38:41]
	v_mfma_f32_16x16x32_bf16 v[38:41], v[118:121], v[174:177], v[38:41]
	v_mfma_f32_16x16x32_bf16 v[22:25], v[118:121], v[182:185], v[22:25]
	v_mfma_f32_16x16x32_bf16 v[22:25], v[130:133], v[186:189], v[22:25]
	v_mfma_f32_16x16x32_bf16 v[6:9], v[130:133], v[214:217], v[6:9]
	v_mfma_f32_16x16x32_bf16 v[6:9], v[118:121], v[210:213], v[6:9]
	v_mfma_f32_16x16x32_bf16 v[2:5], v[142:145], v[210:213], v[2:5]
	v_mfma_f32_16x16x32_bf16 v[2:5], v[154:157], v[214:217], v[2:5]
	v_mfma_f32_16x16x32_bf16 v[18:21], v[154:157], v[186:189], v[18:21]
	v_mfma_f32_16x16x32_bf16 v[18:21], v[142:145], v[182:185], v[18:21]
	v_mfma_f32_16x16x32_bf16 v[34:37], v[142:145], v[174:177], v[34:37]
	v_mfma_f32_16x16x32_bf16 v[34:37], v[154:157], v[178:181], v[34:37]
	v_mfma_f32_16x16x32_bf16 v[50:53], v[154:157], v[170:173], v[50:53]
	v_mfma_f32_16x16x32_bf16 v[50:53], v[142:145], v[158:161], v[50:53]
	s_setprio 0
	s_barrier
	s_add_i32 s41, s41, 2
	s_add_u32 s7, s7, 0x100
	s_addc_u32 s23, s23, 0
	s_cmpk_gt_u32 s41, 0x55
	s_mov_b64 s[8:9], s[64:65]
	s_cbranch_scc1 .LBB0_648
